# static s_setprio 1 for waves 4-7 inside the dense attention loop (reset at loop exit)
# speedup vs baseline: 1.0068x; 1.0068x over previous
;     ...
;   PLOAD(0); asm volatile("s_waitcnt vmcnt(0)" ::: "memory"); PWRITE(0); __syncthreads();
;   qkt(pA0, pA1, KSUB(0, 0), qr, r32, hi); partialSM(pA0, pA1, m_reg, mnA, alA);
.LBB0_486:
	v_add_u32_e32 v180, 0x10000, v162
	s_add_u32 s100, s98, 0xa8000
	s_addc_u32 s101, s99, 0
	s_mov_b64 s[0:1], s[98:99]
	s_mov_b64 s[4:5], s[100:101]
	v_mov_b32_e32 v169, 0
	v_mov_b32_e32 v219, 0
	v_mov_b32_e32 v222, 0
	v_mov_b32_e32 v254, 0
	s_mov_b32 s44, 0
	global_load_dwordx4 v[246:249], v183, s[98:99]
	global_load_dwordx4 v[250:253], v183, s[100:101]
	s_add_u32 s98, s98, 0x150000
	s_addc_u32 s99, s99, 0
	s_add_u32 s100, s100, 0x150000
	s_addc_u32 s101, s101, 0
	s_waitcnt vmcnt(0)
	ds_write_b128 v181, v[246:249] offset:32768
	ds_write_b128 v181, v[250:253] offset:40960
	ds_read_b128 v[200:203], v172 offset:16384
	ds_read_b128 v[204:207], v172 offset:24576
	ds_read_b128 v[208:211], v173 offset:16384
	ds_read_b128 v[212:215], v173 offset:24576
	ds_read_b128 v[230:233], v174 offset:16384
	ds_read_b128 v[234:237], v174 offset:24576
	ds_read_b128 v[238:241], v175 offset:16384
	ds_read_b128 v[242:245], v175 offset:24576
	s_waitcnt lgkmcnt(8)
	s_barrier
	v_readfirstlane_b32 s44, v218
	s_nop 3
	s_cmp_ge_u32 s44, 0x100
	s_mov_b32 s44, 0
	s_cbranch_scc0 .Lprio_done
	s_setprio 1
.Lprio_done:
.Ldense_loop:
	s_waitcnt lgkmcnt(7)
	v_mfma_f32_32x32x16_bf16 v[128:143], v[200:203], v[124:127], 0
	ds_read_b128 v[200:203], v176 offset:16384
	v_cvt_pk_bf16_f32 v184, v64, v65
	v_add_f32_e32 v169, v169, v64
	v_add_f32_e32 v219, v219, v65
	global_load_dwordx4 v[246:249], v183, s[98:99]
	s_waitcnt lgkmcnt(7)
	v_mfma_f32_32x32x16_bf16 v[144:159], v[204:207], v[124:127], 0
	ds_read_b128 v[204:207], v176 offset:24576
	v_cvt_pk_bf16_f32 v185, v66, v67
	v_add_f32_e32 v222, v222, v66
	v_add_f32_e32 v254, v254, v67
	s_waitcnt lgkmcnt(7)
	v_mfma_f32_32x32x16_bf16 v[128:143], v[208:211], v[120:123], v[128:143]
	ds_read_b128 v[208:211], v177 offset:16384
	v_cvt_pk_bf16_f32 v186, v68, v69
	v_add_f32_e32 v169, v169, v68
	v_add_f32_e32 v219, v219, v69
	global_load_dwordx4 v[250:253], v183, s[100:101]
	s_add_u32 s98, s98, 0x150000
	s_addc_u32 s99, s99, 0
	s_add_u32 s100, s100, 0x150000
	s_addc_u32 s101, s101, 0
	s_waitcnt lgkmcnt(7)
	v_mfma_f32_32x32x16_bf16 v[144:159], v[212:215], v[120:123], v[144:159]
	ds_read_b128 v[212:215], v177 offset:24576
	v_cvt_pk_bf16_f32 v187, v70, v71
	v_add_f32_e32 v222, v222, v70
	v_add_f32_e32 v254, v254, v71
	s_waitcnt lgkmcnt(7)
	v_mfma_f32_32x32x16_bf16 v[128:143], v[230:233], v[116:119], v[128:143]
	ds_read_b128 v[230:233], v178 offset:16384
	v_cvt_pk_bf16_f32 v188, v72, v73
	v_add_f32_e32 v169, v169, v72
	v_add_f32_e32 v219, v219, v73
	v_permlane32_swap_b32_e32 v184, v186
	global_load_dwordx4 v[164:167], v183, s[0:1] offset:512
	s_waitcnt lgkmcnt(7)
	v_mfma_f32_32x32x16_bf16 v[144:159], v[234:237], v[116:119], v[144:159]
	ds_read_b128 v[234:237], v178 offset:24576
	v_cvt_pk_bf16_f32 v189, v74, v75
	v_add_f32_e32 v222, v222, v74
	v_add_f32_e32 v254, v254, v75
	v_permlane32_swap_b32_e32 v185, v187
	s_waitcnt lgkmcnt(7)
	v_mfma_f32_32x32x16_bf16 v[128:143], v[238:241], v[112:115], v[128:143]
	ds_read_b128 v[238:241], v179 offset:16384
	v_cvt_pk_bf16_f32 v190, v76, v77
	v_add_f32_e32 v169, v169, v76
	v_add_f32_e32 v219, v219, v77
	global_load_dwordx4 v[160:163], v183, s[4:5] offset:512
	s_add_u32 s0, s0, 0x150000
	s_addc_u32 s1, s1, 0
	s_add_u32 s4, s4, 0x150000
	s_addc_u32 s5, s5, 0
	s_waitcnt lgkmcnt(7)
	v_mfma_f32_32x32x16_bf16 v[144:159], v[242:245], v[112:115], v[144:159]
	ds_read_b128 v[242:245], v179 offset:24576
	v_cvt_pk_bf16_f32 v191, v78, v79
	v_add_f32_e32 v222, v222, v78
	v_add_f32_e32 v254, v254, v79
	s_waitcnt lgkmcnt(7)
	v_mfma_f32_32x32x16_bf16 v[128:143], v[200:203], v[108:111], v[128:143]
	v_cvt_pk_bf16_f32 v192, v80, v81
	v_add_f32_e32 v169, v169, v80
	v_add_f32_e32 v219, v219, v81
	v_permlane32_swap_b32_e32 v188, v190
	s_waitcnt lgkmcnt(6)
	v_mfma_f32_32x32x16_bf16 v[144:159], v[204:207], v[108:111], v[144:159]
	v_cvt_pk_bf16_f32 v193, v82, v83
	v_add_f32_e32 v222, v222, v82
	v_add_f32_e32 v254, v254, v83
	v_permlane32_swap_b32_e32 v189, v191
	s_waitcnt lgkmcnt(5)
	v_mfma_f32_32x32x16_bf16 v[128:143], v[208:211], v[104:107], v[128:143]
	v_cvt_pk_bf16_f32 v194, v84, v85
	v_add_f32_e32 v169, v169, v84
	v_add_f32_e32 v219, v219, v85
	s_waitcnt lgkmcnt(4)
	v_mfma_f32_32x32x16_bf16 v[144:159], v[212:215], v[104:107], v[144:159]
	ds_read_b64_tr_b16 v[200:201], v182 offset:0
	ds_read_b64_tr_b16 v[202:203], v182 offset:2048
	v_cvt_pk_bf16_f32 v195, v86, v87
	v_add_f32_e32 v222, v222, v86
	v_add_f32_e32 v254, v254, v87
	s_waitcnt lgkmcnt(5)
	v_mfma_f32_32x32x16_bf16 v[128:143], v[230:233], v[100:103], v[128:143]
	ds_read_b64_tr_b16 v[204:205], v182 offset:4096
	ds_read_b64_tr_b16 v[206:207], v182 offset:6144
	v_cvt_pk_bf16_f32 v196, v88, v89
	v_add_f32_e32 v169, v169, v88
	v_add_f32_e32 v219, v219, v89
	v_permlane32_swap_b32_e32 v192, v194
	s_waitcnt lgkmcnt(6)
	v_mfma_f32_32x32x16_bf16 v[144:159], v[234:237], v[100:103], v[144:159]
	ds_read_b64_tr_b16 v[208:209], v182 offset:8192
	ds_read_b64_tr_b16 v[210:211], v182 offset:10240
	v_cvt_pk_bf16_f32 v197, v90, v91
	v_add_f32_e32 v222, v222, v90
	v_add_f32_e32 v254, v254, v91
	v_permlane32_swap_b32_e32 v193, v195
	s_waitcnt lgkmcnt(7)
	v_mfma_f32_32x32x16_bf16 v[128:143], v[238:241], v[96:99], v[128:143]
	ds_read_b64_tr_b16 v[212:213], v182 offset:12288
	ds_read_b64_tr_b16 v[214:215], v182 offset:14336
	v_cvt_pk_bf16_f32 v198, v92, v93
	v_add_f32_e32 v169, v169, v92
	v_add_f32_e32 v219, v219, v93
	s_waitcnt lgkmcnt(8)
	v_mfma_f32_32x32x16_bf16 v[144:159], v[242:245], v[96:99], v[144:159]
	ds_read_b64_tr_b16 v[230:231], v182 offset:512
	ds_read_b64_tr_b16 v[232:233], v182 offset:2560
	v_cvt_pk_bf16_f32 v199, v94, v95
	v_add_f32_e32 v222, v222, v94
	v_add_f32_e32 v254, v254, v95
	v_permlane32_swap_b32_e32 v196, v198
	v_permlane32_swap_b32_e32 v197, v199
	s_waitcnt lgkmcnt(8)
; #define SBAR() __builtin_amdgcn_sched_barrier(0)
; template <int D0> __device__ __forceinline__ void pv_one(f32x16& od, int vb, bf16x8 pa0, bf16x8 pa1, bf16x8 pa2, bf16x8 pa3) {
;   const s16x4 l0 = tr_read<v_rd_off(D0, 0, 0)>(vb), h0 = tr_read<v_rd_off(D0, 0, 1)>(vb), l1 = tr_read<v_rd_off(D0, 1, 0)>(vb), h1 = tr_read<v_rd_off(D0, 1, 1)>(vb);
;   const s16x4 l2 = tr_read<v_rd_off(D0, 2, 0)>(vb), h2 = tr_read<v_rd_off(D0, 2, 1)>(vb), l3 = tr_read<v_rd_off(D0, 3, 0)>(vb), h3 = tr_read<v_rd_off(D0, 3, 1)>(vb);
;   asm volatile("s_waitcnt lgkmcnt(0)" ::: "memory"); SBAR();
;     ...
;   od = __builtin_amdgcn_mfma_f32_32x32x16_bf16(pa0, PK(l0, h0), od, 0, 0, 0);
;   od = __builtin_amdgcn_mfma_f32_32x32x16_bf16(pa1, PK(l1, h1), od, 0, 0, 0);
;   od = __builtin_amdgcn_mfma_f32_32x32x16_bf16(pa2, PK(l2, h2), od, 0, 0, 0);
;   od = __builtin_amdgcn_mfma_f32_32x32x16_bf16(pa3, PK(l3, h3), od, 0, 0, 0);
;     ...
; }
; __device__ __forceinline__ void pv_d0(f32x16* o, int vb, bf16x8 pa0, bf16x8 pa1, bf16x8 pa2, bf16x8 pa3) {
;   pv_one<0>(o[0], vb, pa0, pa1, pa2, pa3); pv_one<1>(o[1], vb, pa0, pa1, pa2, pa3); pv_one<2>(o[2], vb, pa0, pa1, pa2, pa3); pv_one<3>(o[3], vb, pa0, pa1, pa2, pa3);
	v_mfma_f32_32x32x16_bf16 v[0:15], v[184:187], v[200:203], v[0:15]
	ds_read_b64_tr_b16 v[234:235], v182 offset:4608
	ds_read_b64_tr_b16 v[236:237], v182 offset:6656
	v_exp_f32_e32 v128, v128
	v_exp_f32_e32 v129, v129
	s_waitcnt lgkmcnt(8)
	v_mfma_f32_32x32x16_bf16 v[0:15], v[188:191], v[204:207], v[0:15]
	ds_read_b64_tr_b16 v[238:239], v182 offset:8704
	ds_read_b64_tr_b16 v[240:241], v182 offset:10752
	v_exp_f32_e32 v130, v130
	v_exp_f32_e32 v131, v131
	s_waitcnt vmcnt(3)
	ds_write_b128 v181, v[246:249] offset:49152
	s_waitcnt lgkmcnt(9)
	v_mfma_f32_32x32x16_bf16 v[0:15], v[192:195], v[208:211], v[0:15]
	ds_read_b64_tr_b16 v[242:243], v182 offset:12800
	ds_read_b64_tr_b16 v[244:245], v182 offset:14848
	v_exp_f32_e32 v132, v132
	v_exp_f32_e32 v133, v133
	s_waitcnt lgkmcnt(9)
	v_mfma_f32_32x32x16_bf16 v[0:15], v[196:199], v[212:215], v[0:15]
	ds_read_b64_tr_b16 v[200:201], v182 offset:1024
	ds_read_b64_tr_b16 v[202:203], v182 offset:3072
	v_exp_f32_e32 v134, v134
	v_exp_f32_e32 v135, v135
	s_waitcnt vmcnt(2)
	ds_write_b128 v181, v[250:253] offset:57344
	s_waitcnt lgkmcnt(10)
	v_mfma_f32_32x32x16_bf16 v[48:63], v[184:187], v[230:233], v[48:63]
	ds_read_b64_tr_b16 v[204:205], v182 offset:5120
	ds_read_b64_tr_b16 v[206:207], v182 offset:7168
	v_exp_f32_e32 v136, v136
	v_exp_f32_e32 v137, v137
	s_waitcnt lgkmcnt(10)
	v_mfma_f32_32x32x16_bf16 v[48:63], v[188:191], v[234:237], v[48:63]
	ds_read_b64_tr_b16 v[208:209], v182 offset:9216
	ds_read_b64_tr_b16 v[210:211], v182 offset:11264
	v_exp_f32_e32 v138, v138
	v_exp_f32_e32 v139, v139
	s_waitcnt vmcnt(1)
	ds_write_b128 v180, v[164:167] offset:32768
	s_waitcnt lgkmcnt(11)
	v_mfma_f32_32x32x16_bf16 v[48:63], v[192:195], v[238:241], v[48:63]
	ds_read_b64_tr_b16 v[212:213], v182 offset:13312
	ds_read_b64_tr_b16 v[214:215], v182 offset:15360
	v_exp_f32_e32 v140, v140
	v_exp_f32_e32 v141, v141
	s_waitcnt lgkmcnt(10)
	v_mfma_f32_32x32x16_bf16 v[48:63], v[196:199], v[242:245], v[48:63]
	ds_read_b64_tr_b16 v[230:231], v182 offset:1536
	ds_read_b64_tr_b16 v[232:233], v182 offset:3584
	v_exp_f32_e32 v142, v142
	v_exp_f32_e32 v143, v143
	s_waitcnt vmcnt(0)
	ds_write_b128 v180, v[160:163] offset:40960
	s_waitcnt lgkmcnt(11)
	v_mfma_f32_32x32x16_bf16 v[32:47], v[184:187], v[200:203], v[32:47]
	ds_read_b64_tr_b16 v[234:235], v182 offset:5632
	ds_read_b64_tr_b16 v[236:237], v182 offset:7680
	ds_read_b128 v[200:203], v172 offset:32768
	v_exp_f32_e32 v144, v144
	v_exp_f32_e32 v145, v145
	s_waitcnt lgkmcnt(11)
	v_mfma_f32_32x32x16_bf16 v[32:47], v[188:191], v[204:207], v[32:47]
	ds_read_b64_tr_b16 v[238:239], v182 offset:9728
	ds_read_b64_tr_b16 v[240:241], v182 offset:11776
	ds_read_b128 v[204:207], v172 offset:40960
	v_exp_f32_e32 v146, v146
	v_exp_f32_e32 v147, v147
	s_waitcnt lgkmcnt(12)
	v_mfma_f32_32x32x16_bf16 v[32:47], v[192:195], v[208:211], v[32:47]
	ds_read_b64_tr_b16 v[242:243], v182 offset:13824
	ds_read_b64_tr_b16 v[244:245], v182 offset:15872
	ds_read_b128 v[208:211], v173 offset:32768
	v_exp_f32_e32 v148, v148
	v_exp_f32_e32 v149, v149
	s_waitcnt lgkmcnt(12)
	v_mfma_f32_32x32x16_bf16 v[32:47], v[196:199], v[212:215], v[32:47]
	ds_read_b128 v[212:215], v173 offset:40960
	v_exp_f32_e32 v150, v150
	v_exp_f32_e32 v151, v151
	s_waitcnt lgkmcnt(11)
	v_mfma_f32_32x32x16_bf16 v[16:31], v[184:187], v[230:233], v[16:31]
	ds_read_b128 v[230:233], v174 offset:32768
	v_exp_f32_e32 v152, v152
	v_exp_f32_e32 v153, v153
	s_waitcnt lgkmcnt(9)
	v_mfma_f32_32x32x16_bf16 v[16:31], v[188:191], v[234:237], v[16:31]
	ds_read_b128 v[234:237], v174 offset:40960
	v_exp_f32_e32 v154, v154
	v_exp_f32_e32 v155, v155
	s_waitcnt lgkmcnt(7)
	v_mfma_f32_32x32x16_bf16 v[16:31], v[192:195], v[238:241], v[16:31]
	ds_read_b128 v[238:241], v175 offset:32768
	v_exp_f32_e32 v156, v156
	v_exp_f32_e32 v157, v157
	s_waitcnt lgkmcnt(5)
	v_mfma_f32_32x32x16_bf16 v[16:31], v[196:199], v[242:245], v[16:31]
	ds_read_b128 v[242:245], v175 offset:40960
	v_exp_f32_e32 v158, v158
	v_exp_f32_e32 v159, v159
	s_barrier
	v_mfma_f32_32x32x16_bf16 v[64:79], v[200:203], v[124:127], 0
	ds_read_b128 v[200:203], v176 offset:32768
	v_cvt_pk_bf16_f32 v184, v128, v129
	v_add_f32_e32 v169, v169, v128
	v_add_f32_e32 v219, v219, v129
	global_load_dwordx4 v[246:249], v183, s[98:99]
	v_mfma_f32_32x32x16_bf16 v[80:95], v[204:207], v[124:127], 0
	ds_read_b128 v[204:207], v176 offset:40960
	v_cvt_pk_bf16_f32 v185, v130, v131
	v_add_f32_e32 v222, v222, v130
	v_add_f32_e32 v254, v254, v131
	s_waitcnt lgkmcnt(7)
	v_mfma_f32_32x32x16_bf16 v[64:79], v[208:211], v[120:123], v[64:79]
	ds_read_b128 v[208:211], v177 offset:32768
	v_cvt_pk_bf16_f32 v186, v132, v133
	v_add_f32_e32 v169, v169, v132
	v_add_f32_e32 v219, v219, v133
	global_load_dwordx4 v[250:253], v183, s[100:101]
	s_add_u32 s98, s98, 0x150000
	s_addc_u32 s99, s99, 0
	s_add_u32 s100, s100, 0x150000
	s_addc_u32 s101, s101, 0
	s_waitcnt lgkmcnt(7)
	v_mfma_f32_32x32x16_bf16 v[80:95], v[212:215], v[120:123], v[80:95]
	ds_read_b128 v[212:215], v177 offset:40960
	v_cvt_pk_bf16_f32 v187, v134, v135
	v_add_f32_e32 v222, v222, v134
	v_add_f32_e32 v254, v254, v135
	s_waitcnt lgkmcnt(7)
	v_mfma_f32_32x32x16_bf16 v[64:79], v[230:233], v[116:119], v[64:79]
	ds_read_b128 v[230:233], v178 offset:32768
	v_cvt_pk_bf16_f32 v188, v136, v137
	v_add_f32_e32 v169, v169, v136
	v_add_f32_e32 v219, v219, v137
	v_permlane32_swap_b32_e32 v184, v186
	global_load_dwordx4 v[164:167], v183, s[0:1] offset:512
	s_waitcnt lgkmcnt(7)
	v_mfma_f32_32x32x16_bf16 v[80:95], v[234:237], v[116:119], v[80:95]
	ds_read_b128 v[234:237], v178 offset:40960
	v_cvt_pk_bf16_f32 v189, v138, v139
	v_add_f32_e32 v222, v222, v138
	v_add_f32_e32 v254, v254, v139
	v_permlane32_swap_b32_e32 v185, v187
	s_waitcnt lgkmcnt(7)
; #define SBAR() __builtin_amdgcn_sched_barrier(0)
; template <int D0> __device__ __forceinline__ void pv_one(f32x16& od, int vb, bf16x8 pa0, bf16x8 pa1, bf16x8 pa2, bf16x8 pa3) {
;   const s16x4 l0 = tr_read<v_rd_off(D0, 0, 0)>(vb), h0 = tr_read<v_rd_off(D0, 0, 1)>(vb), l1 = tr_read<v_rd_off(D0, 1, 0)>(vb), h1 = tr_read<v_rd_off(D0, 1, 1)>(vb);
;   const s16x4 l2 = tr_read<v_rd_off(D0, 2, 0)>(vb), h2 = tr_read<v_rd_off(D0, 2, 1)>(vb), l3 = tr_read<v_rd_off(D0, 3, 0)>(vb), h3 = tr_read<v_rd_off(D0, 3, 1)>(vb);
;   asm volatile("s_waitcnt lgkmcnt(0)" ::: "memory"); SBAR();
;     ...
;   od = __builtin_amdgcn_mfma_f32_32x32x16_bf16(pa0, PK(l0, h0), od, 0, 0, 0);
;   od = __builtin_amdgcn_mfma_f32_32x32x16_bf16(pa1, PK(l1, h1), od, 0, 0, 0);
;   od = __builtin_amdgcn_mfma_f32_32x32x16_bf16(pa2, PK(l2, h2), od, 0, 0, 0);
;   od = __builtin_amdgcn_mfma_f32_32x32x16_bf16(pa3, PK(l3, h3), od, 0, 0, 0);
;     ...
; }
; __device__ __forceinline__ void pv_d0(f32x16* o, int vb, bf16x8 pa0, bf16x8 pa1, bf16x8 pa2, bf16x8 pa3) {
;   pv_one<0>(o[0], vb, pa0, pa1, pa2, pa3); pv_one<1>(o[1], vb, pa0, pa1, pa2, pa3); pv_one<2>(o[2], vb, pa0, pa1, pa2, pa3); pv_one<3>(o[3], vb, pa0, pa1, pa2, pa3);
	v_mfma_f32_32x32x16_bf16 v[64:79], v[238:241], v[112:115], v[64:79]
	ds_read_b128 v[238:241], v179 offset:32768
	v_cvt_pk_bf16_f32 v190, v140, v141
	v_add_f32_e32 v169, v169, v140
	v_add_f32_e32 v219, v219, v141
	global_load_dwordx4 v[160:163], v183, s[4:5] offset:512
	s_add_u32 s0, s0, 0x150000
	s_addc_u32 s1, s1, 0
	s_add_u32 s4, s4, 0x150000
	s_addc_u32 s5, s5, 0
	s_waitcnt lgkmcnt(7)
	v_mfma_f32_32x32x16_bf16 v[80:95], v[242:245], v[112:115], v[80:95]
	ds_read_b128 v[242:245], v179 offset:40960
	v_cvt_pk_bf16_f32 v191, v142, v143
	v_add_f32_e32 v222, v222, v142
	v_add_f32_e32 v254, v254, v143
	s_waitcnt lgkmcnt(7)
	v_mfma_f32_32x32x16_bf16 v[64:79], v[200:203], v[108:111], v[64:79]
	v_cvt_pk_bf16_f32 v192, v144, v145
	v_add_f32_e32 v169, v169, v144
	v_add_f32_e32 v219, v219, v145
	v_permlane32_swap_b32_e32 v188, v190
	s_waitcnt lgkmcnt(6)
	v_mfma_f32_32x32x16_bf16 v[80:95], v[204:207], v[108:111], v[80:95]
	v_cvt_pk_bf16_f32 v193, v146, v147
	v_add_f32_e32 v222, v222, v146
	v_add_f32_e32 v254, v254, v147
	v_permlane32_swap_b32_e32 v189, v191
	s_waitcnt lgkmcnt(5)
	v_mfma_f32_32x32x16_bf16 v[64:79], v[208:211], v[104:107], v[64:79]
	v_cvt_pk_bf16_f32 v194, v148, v149
	v_add_f32_e32 v169, v169, v148
	v_add_f32_e32 v219, v219, v149
	s_waitcnt lgkmcnt(4)
	v_mfma_f32_32x32x16_bf16 v[80:95], v[212:215], v[104:107], v[80:95]
	ds_read_b64_tr_b16 v[200:201], v182 offset:16384
	ds_read_b64_tr_b16 v[202:203], v182 offset:18432
	v_cvt_pk_bf16_f32 v195, v150, v151
	v_add_f32_e32 v222, v222, v150
	v_add_f32_e32 v254, v254, v151
	s_waitcnt lgkmcnt(5)
	v_mfma_f32_32x32x16_bf16 v[64:79], v[230:233], v[100:103], v[64:79]
	ds_read_b64_tr_b16 v[204:205], v182 offset:20480
	ds_read_b64_tr_b16 v[206:207], v182 offset:22528
	v_cvt_pk_bf16_f32 v196, v152, v153
	v_add_f32_e32 v169, v169, v152
	v_add_f32_e32 v219, v219, v153
	v_permlane32_swap_b32_e32 v192, v194
	s_waitcnt lgkmcnt(6)
	v_mfma_f32_32x32x16_bf16 v[80:95], v[234:237], v[100:103], v[80:95]
	ds_read_b64_tr_b16 v[208:209], v182 offset:24576
	ds_read_b64_tr_b16 v[210:211], v182 offset:26624
	v_cvt_pk_bf16_f32 v197, v154, v155
	v_add_f32_e32 v222, v222, v154
	v_add_f32_e32 v254, v254, v155
	v_permlane32_swap_b32_e32 v193, v195
	s_waitcnt lgkmcnt(7)
	v_mfma_f32_32x32x16_bf16 v[64:79], v[238:241], v[96:99], v[64:79]
	ds_read_b64_tr_b16 v[212:213], v182 offset:28672
	ds_read_b64_tr_b16 v[214:215], v182 offset:30720
	v_cvt_pk_bf16_f32 v198, v156, v157
	v_add_f32_e32 v169, v169, v156
	v_add_f32_e32 v219, v219, v157
	s_waitcnt lgkmcnt(8)
	v_mfma_f32_32x32x16_bf16 v[80:95], v[242:245], v[96:99], v[80:95]
	ds_read_b64_tr_b16 v[230:231], v182 offset:16896
	ds_read_b64_tr_b16 v[232:233], v182 offset:18944
	v_cvt_pk_bf16_f32 v199, v158, v159
	v_add_f32_e32 v222, v222, v158
	v_add_f32_e32 v254, v254, v159
	v_permlane32_swap_b32_e32 v196, v198
	v_permlane32_swap_b32_e32 v197, v199
	s_waitcnt lgkmcnt(8)
	v_mfma_f32_32x32x16_bf16 v[0:15], v[184:187], v[200:203], v[0:15]
	ds_read_b64_tr_b16 v[234:235], v182 offset:20992
	ds_read_b64_tr_b16 v[236:237], v182 offset:23040
	v_exp_f32_e32 v64, v64
	v_exp_f32_e32 v65, v65
	s_waitcnt lgkmcnt(8)
	v_mfma_f32_32x32x16_bf16 v[0:15], v[188:191], v[204:207], v[0:15]
	ds_read_b64_tr_b16 v[238:239], v182 offset:25088
	ds_read_b64_tr_b16 v[240:241], v182 offset:27136
	v_exp_f32_e32 v66, v66
	v_exp_f32_e32 v67, v67
	s_waitcnt vmcnt(3)
	ds_write_b128 v181, v[246:249] offset:0
	s_waitcnt lgkmcnt(9)
	v_mfma_f32_32x32x16_bf16 v[0:15], v[192:195], v[208:211], v[0:15]
	ds_read_b64_tr_b16 v[242:243], v182 offset:29184
	ds_read_b64_tr_b16 v[244:245], v182 offset:31232
	v_exp_f32_e32 v68, v68
	v_exp_f32_e32 v69, v69
	s_waitcnt lgkmcnt(9)
	v_mfma_f32_32x32x16_bf16 v[0:15], v[196:199], v[212:215], v[0:15]
	ds_read_b64_tr_b16 v[200:201], v182 offset:17408
	ds_read_b64_tr_b16 v[202:203], v182 offset:19456
	v_exp_f32_e32 v70, v70
	v_exp_f32_e32 v71, v71
	s_waitcnt vmcnt(2)
	ds_write_b128 v181, v[250:253] offset:8192
	s_waitcnt lgkmcnt(10)
	v_mfma_f32_32x32x16_bf16 v[48:63], v[184:187], v[230:233], v[48:63]
	ds_read_b64_tr_b16 v[204:205], v182 offset:21504
	ds_read_b64_tr_b16 v[206:207], v182 offset:23552
	v_exp_f32_e32 v72, v72
	v_exp_f32_e32 v73, v73
	s_waitcnt lgkmcnt(10)
	v_mfma_f32_32x32x16_bf16 v[48:63], v[188:191], v[234:237], v[48:63]
	ds_read_b64_tr_b16 v[208:209], v182 offset:25600
	ds_read_b64_tr_b16 v[210:211], v182 offset:27648
	v_exp_f32_e32 v74, v74
	v_exp_f32_e32 v75, v75
	s_waitcnt vmcnt(1)
	ds_write_b128 v180, v[164:167] offset:49152
	s_waitcnt lgkmcnt(11)
	v_mfma_f32_32x32x16_bf16 v[48:63], v[192:195], v[238:241], v[48:63]
	ds_read_b64_tr_b16 v[212:213], v182 offset:29696
	ds_read_b64_tr_b16 v[214:215], v182 offset:31744
	v_exp_f32_e32 v76, v76
	v_exp_f32_e32 v77, v77
	s_waitcnt lgkmcnt(10)
	v_mfma_f32_32x32x16_bf16 v[48:63], v[196:199], v[242:245], v[48:63]
	ds_read_b64_tr_b16 v[230:231], v182 offset:17920
	ds_read_b64_tr_b16 v[232:233], v182 offset:19968
	v_exp_f32_e32 v78, v78
	v_exp_f32_e32 v79, v79
	s_waitcnt vmcnt(0)
	ds_write_b128 v180, v[160:163] offset:57344
	s_waitcnt lgkmcnt(11)
	v_mfma_f32_32x32x16_bf16 v[32:47], v[184:187], v[200:203], v[32:47]
	ds_read_b64_tr_b16 v[234:235], v182 offset:22016
	ds_read_b64_tr_b16 v[236:237], v182 offset:24064
	ds_read_b128 v[200:203], v172 offset:49152
	v_exp_f32_e32 v80, v80
	v_exp_f32_e32 v81, v81
	s_waitcnt lgkmcnt(11)
	v_mfma_f32_32x32x16_bf16 v[32:47], v[188:191], v[204:207], v[32:47]
	ds_read_b64_tr_b16 v[238:239], v182 offset:26112
	ds_read_b64_tr_b16 v[240:241], v182 offset:28160
	ds_read_b128 v[204:207], v172 offset:57344
	v_exp_f32_e32 v82, v82
	v_exp_f32_e32 v83, v83
	s_waitcnt lgkmcnt(12)
	v_mfma_f32_32x32x16_bf16 v[32:47], v[192:195], v[208:211], v[32:47]
	ds_read_b64_tr_b16 v[242:243], v182 offset:30208
	ds_read_b64_tr_b16 v[244:245], v182 offset:32256
	ds_read_b128 v[208:211], v173 offset:49152
	v_exp_f32_e32 v84, v84
	v_exp_f32_e32 v85, v85
	s_waitcnt lgkmcnt(12)
	v_mfma_f32_32x32x16_bf16 v[32:47], v[196:199], v[212:215], v[32:47]
	ds_read_b128 v[212:215], v173 offset:57344
	v_exp_f32_e32 v86, v86
	v_exp_f32_e32 v87, v87
	s_waitcnt lgkmcnt(11)
	v_mfma_f32_32x32x16_bf16 v[16:31], v[184:187], v[230:233], v[16:31]
	ds_read_b128 v[230:233], v174 offset:49152
	v_exp_f32_e32 v88, v88
	v_exp_f32_e32 v89, v89
	s_waitcnt lgkmcnt(9)
	v_mfma_f32_32x32x16_bf16 v[16:31], v[188:191], v[234:237], v[16:31]
	ds_read_b128 v[234:237], v174 offset:57344
	v_exp_f32_e32 v90, v90
	v_exp_f32_e32 v91, v91
	s_waitcnt lgkmcnt(7)
	v_mfma_f32_32x32x16_bf16 v[16:31], v[192:195], v[238:241], v[16:31]
	ds_read_b128 v[238:241], v175 offset:49152
	v_exp_f32_e32 v92, v92
	v_exp_f32_e32 v93, v93
	s_waitcnt lgkmcnt(5)
	v_mfma_f32_32x32x16_bf16 v[16:31], v[196:199], v[242:245], v[16:31]
	ds_read_b128 v[242:245], v175 offset:57344
	v_exp_f32_e32 v94, v94
	v_exp_f32_e32 v95, v95
	s_barrier
; #define SBAR() __builtin_amdgcn_sched_barrier(0)
; template <int D0> __device__ __forceinline__ void pv_one(f32x16& od, int vb, bf16x8 pa0, bf16x8 pa1, bf16x8 pa2, bf16x8 pa3) {
;   const s16x4 l0 = tr_read<v_rd_off(D0, 0, 0)>(vb), h0 = tr_read<v_rd_off(D0, 0, 1)>(vb), l1 = tr_read<v_rd_off(D0, 1, 0)>(vb), h1 = tr_read<v_rd_off(D0, 1, 1)>(vb);
;   const s16x4 l2 = tr_read<v_rd_off(D0, 2, 0)>(vb), h2 = tr_read<v_rd_off(D0, 2, 1)>(vb), l3 = tr_read<v_rd_off(D0, 3, 0)>(vb), h3 = tr_read<v_rd_off(D0, 3, 1)>(vb);
;   asm volatile("s_waitcnt lgkmcnt(0)" ::: "memory"); SBAR();
;     ...
;   od = __builtin_amdgcn_mfma_f32_32x32x16_bf16(pa0, PK(l0, h0), od, 0, 0, 0);
;   od = __builtin_amdgcn_mfma_f32_32x32x16_bf16(pa1, PK(l1, h1), od, 0, 0, 0);
;   od = __builtin_amdgcn_mfma_f32_32x32x16_bf16(pa2, PK(l2, h2), od, 0, 0, 0);
;   od = __builtin_amdgcn_mfma_f32_32x32x16_bf16(pa3, PK(l3, h3), od, 0, 0, 0);
;     ...
; }
; __device__ __forceinline__ void pv_d0(f32x16* o, int vb, bf16x8 pa0, bf16x8 pa1, bf16x8 pa2, bf16x8 pa3) {
;   pv_one<0>(o[0], vb, pa0, pa1, pa2, pa3); pv_one<1>(o[1], vb, pa0, pa1, pa2, pa3); pv_one<2>(o[2], vb, pa0, pa1, pa2, pa3); pv_one<3>(o[3], vb, pa0, pa1, pa2, pa3);
	v_mfma_f32_32x32x16_bf16 v[128:143], v[200:203], v[124:127], 0
	ds_read_b128 v[200:203], v176 offset:49152
	v_cvt_pk_bf16_f32 v184, v64, v65
	v_add_f32_e32 v169, v169, v64
	v_add_f32_e32 v219, v219, v65
	global_load_dwordx4 v[246:249], v183, s[98:99]
	v_mfma_f32_32x32x16_bf16 v[144:159], v[204:207], v[124:127], 0
	ds_read_b128 v[204:207], v176 offset:57344
	v_cvt_pk_bf16_f32 v185, v66, v67
	v_add_f32_e32 v222, v222, v66
	v_add_f32_e32 v254, v254, v67
	s_waitcnt lgkmcnt(7)
	v_mfma_f32_32x32x16_bf16 v[128:143], v[208:211], v[120:123], v[128:143]
	ds_read_b128 v[208:211], v177 offset:49152
	v_cvt_pk_bf16_f32 v186, v68, v69
	v_add_f32_e32 v169, v169, v68
	v_add_f32_e32 v219, v219, v69
	global_load_dwordx4 v[250:253], v183, s[100:101]
	s_add_u32 s98, s98, 0x150000
	s_addc_u32 s99, s99, 0
	s_add_u32 s100, s100, 0x150000
	s_addc_u32 s101, s101, 0
	s_waitcnt lgkmcnt(7)
	v_mfma_f32_32x32x16_bf16 v[144:159], v[212:215], v[120:123], v[144:159]
	ds_read_b128 v[212:215], v177 offset:57344
	v_cvt_pk_bf16_f32 v187, v70, v71
	v_add_f32_e32 v222, v222, v70
	v_add_f32_e32 v254, v254, v71
	s_waitcnt lgkmcnt(7)
	v_mfma_f32_32x32x16_bf16 v[128:143], v[230:233], v[116:119], v[128:143]
	ds_read_b128 v[230:233], v178 offset:49152
	v_cvt_pk_bf16_f32 v188, v72, v73
	v_add_f32_e32 v169, v169, v72
	v_add_f32_e32 v219, v219, v73
	v_permlane32_swap_b32_e32 v184, v186
	global_load_dwordx4 v[164:167], v183, s[0:1] offset:512
	s_waitcnt lgkmcnt(7)
	v_mfma_f32_32x32x16_bf16 v[144:159], v[234:237], v[116:119], v[144:159]
	ds_read_b128 v[234:237], v178 offset:57344
	v_cvt_pk_bf16_f32 v189, v74, v75
	v_add_f32_e32 v222, v222, v74
	v_add_f32_e32 v254, v254, v75
	v_permlane32_swap_b32_e32 v185, v187
	s_waitcnt lgkmcnt(7)
	v_mfma_f32_32x32x16_bf16 v[128:143], v[238:241], v[112:115], v[128:143]
	ds_read_b128 v[238:241], v179 offset:49152
	v_cvt_pk_bf16_f32 v190, v76, v77
	v_add_f32_e32 v169, v169, v76
	v_add_f32_e32 v219, v219, v77
	global_load_dwordx4 v[160:163], v183, s[4:5] offset:512
	s_add_u32 s0, s0, 0x150000
	s_addc_u32 s1, s1, 0
	s_add_u32 s4, s4, 0x150000
	s_addc_u32 s5, s5, 0
	s_waitcnt lgkmcnt(7)
	v_mfma_f32_32x32x16_bf16 v[144:159], v[242:245], v[112:115], v[144:159]
	ds_read_b128 v[242:245], v179 offset:57344
	v_cvt_pk_bf16_f32 v191, v78, v79
	v_add_f32_e32 v222, v222, v78
	v_add_f32_e32 v254, v254, v79
	s_waitcnt lgkmcnt(7)
	v_mfma_f32_32x32x16_bf16 v[128:143], v[200:203], v[108:111], v[128:143]
	v_cvt_pk_bf16_f32 v192, v80, v81
	v_add_f32_e32 v169, v169, v80
	v_add_f32_e32 v219, v219, v81
	v_permlane32_swap_b32_e32 v188, v190
	s_waitcnt lgkmcnt(6)
	v_mfma_f32_32x32x16_bf16 v[144:159], v[204:207], v[108:111], v[144:159]
	v_cvt_pk_bf16_f32 v193, v82, v83
	v_add_f32_e32 v222, v222, v82
	v_add_f32_e32 v254, v254, v83
	v_permlane32_swap_b32_e32 v189, v191
	s_waitcnt lgkmcnt(5)
	v_mfma_f32_32x32x16_bf16 v[128:143], v[208:211], v[104:107], v[128:143]
	v_cvt_pk_bf16_f32 v194, v84, v85
	v_add_f32_e32 v169, v169, v84
	v_add_f32_e32 v219, v219, v85
	s_waitcnt lgkmcnt(4)
	v_mfma_f32_32x32x16_bf16 v[144:159], v[212:215], v[104:107], v[144:159]
	ds_read_b64_tr_b16 v[200:201], v182 offset:32768
	ds_read_b64_tr_b16 v[202:203], v182 offset:34816
	v_cvt_pk_bf16_f32 v195, v86, v87
	v_add_f32_e32 v222, v222, v86
	v_add_f32_e32 v254, v254, v87
	s_waitcnt lgkmcnt(5)
	v_mfma_f32_32x32x16_bf16 v[128:143], v[230:233], v[100:103], v[128:143]
	ds_read_b64_tr_b16 v[204:205], v182 offset:36864
	ds_read_b64_tr_b16 v[206:207], v182 offset:38912
	v_cvt_pk_bf16_f32 v196, v88, v89
	v_add_f32_e32 v169, v169, v88
	v_add_f32_e32 v219, v219, v89
	v_permlane32_swap_b32_e32 v192, v194
	s_waitcnt lgkmcnt(6)
	v_mfma_f32_32x32x16_bf16 v[144:159], v[234:237], v[100:103], v[144:159]
	ds_read_b64_tr_b16 v[208:209], v182 offset:40960
	ds_read_b64_tr_b16 v[210:211], v182 offset:43008
	v_cvt_pk_bf16_f32 v197, v90, v91
	v_add_f32_e32 v222, v222, v90
	v_add_f32_e32 v254, v254, v91
	v_permlane32_swap_b32_e32 v193, v195
	s_waitcnt lgkmcnt(7)
	v_mfma_f32_32x32x16_bf16 v[128:143], v[238:241], v[96:99], v[128:143]
	ds_read_b64_tr_b16 v[212:213], v182 offset:45056
	ds_read_b64_tr_b16 v[214:215], v182 offset:47104
	v_cvt_pk_bf16_f32 v198, v92, v93
	v_add_f32_e32 v169, v169, v92
	v_add_f32_e32 v219, v219, v93
	s_waitcnt lgkmcnt(8)
	v_mfma_f32_32x32x16_bf16 v[144:159], v[242:245], v[96:99], v[144:159]
	ds_read_b64_tr_b16 v[230:231], v182 offset:33280
	ds_read_b64_tr_b16 v[232:233], v182 offset:35328
	v_cvt_pk_bf16_f32 v199, v94, v95
	v_add_f32_e32 v222, v222, v94
	v_add_f32_e32 v254, v254, v95
	v_permlane32_swap_b32_e32 v196, v198
	v_permlane32_swap_b32_e32 v197, v199
	s_waitcnt lgkmcnt(8)
	v_mfma_f32_32x32x16_bf16 v[0:15], v[184:187], v[200:203], v[0:15]
	ds_read_b64_tr_b16 v[234:235], v182 offset:37376
	ds_read_b64_tr_b16 v[236:237], v182 offset:39424
	v_exp_f32_e32 v128, v128
	v_exp_f32_e32 v129, v129
	s_waitcnt lgkmcnt(8)
	v_mfma_f32_32x32x16_bf16 v[0:15], v[188:191], v[204:207], v[0:15]
	ds_read_b64_tr_b16 v[238:239], v182 offset:41472
	ds_read_b64_tr_b16 v[240:241], v182 offset:43520
	v_exp_f32_e32 v130, v130
	v_exp_f32_e32 v131, v131
	s_waitcnt vmcnt(3)
	ds_write_b128 v181, v[246:249] offset:16384
	s_waitcnt lgkmcnt(9)
	v_mfma_f32_32x32x16_bf16 v[0:15], v[192:195], v[208:211], v[0:15]
	ds_read_b64_tr_b16 v[242:243], v182 offset:45568
	ds_read_b64_tr_b16 v[244:245], v182 offset:47616
	v_exp_f32_e32 v132, v132
	v_exp_f32_e32 v133, v133
	s_waitcnt lgkmcnt(9)
	v_mfma_f32_32x32x16_bf16 v[0:15], v[196:199], v[212:215], v[0:15]
	ds_read_b64_tr_b16 v[200:201], v182 offset:33792
	ds_read_b64_tr_b16 v[202:203], v182 offset:35840
	v_exp_f32_e32 v134, v134
	v_exp_f32_e32 v135, v135
	s_waitcnt vmcnt(2)
; #define SBAR() __builtin_amdgcn_sched_barrier(0)
; template <int D0> __device__ __forceinline__ void pv_one(f32x16& od, int vb, bf16x8 pa0, bf16x8 pa1, bf16x8 pa2, bf16x8 pa3) {
;   const s16x4 l0 = tr_read<v_rd_off(D0, 0, 0)>(vb), h0 = tr_read<v_rd_off(D0, 0, 1)>(vb), l1 = tr_read<v_rd_off(D0, 1, 0)>(vb), h1 = tr_read<v_rd_off(D0, 1, 1)>(vb);
;   const s16x4 l2 = tr_read<v_rd_off(D0, 2, 0)>(vb), h2 = tr_read<v_rd_off(D0, 2, 1)>(vb), l3 = tr_read<v_rd_off(D0, 3, 0)>(vb), h3 = tr_read<v_rd_off(D0, 3, 1)>(vb);
;   asm volatile("s_waitcnt lgkmcnt(0)" ::: "memory"); SBAR();
;     ...
;   od = __builtin_amdgcn_mfma_f32_32x32x16_bf16(pa0, PK(l0, h0), od, 0, 0, 0);
;   od = __builtin_amdgcn_mfma_f32_32x32x16_bf16(pa1, PK(l1, h1), od, 0, 0, 0);
;   od = __builtin_amdgcn_mfma_f32_32x32x16_bf16(pa2, PK(l2, h2), od, 0, 0, 0);
;   od = __builtin_amdgcn_mfma_f32_32x32x16_bf16(pa3, PK(l3, h3), od, 0, 0, 0);
;     ...
; }
; __device__ __forceinline__ void pv_d0(f32x16* o, int vb, bf16x8 pa0, bf16x8 pa1, bf16x8 pa2, bf16x8 pa3) {
;   pv_one<0>(o[0], vb, pa0, pa1, pa2, pa3); pv_one<1>(o[1], vb, pa0, pa1, pa2, pa3); pv_one<2>(o[2], vb, pa0, pa1, pa2, pa3); pv_one<3>(o[3], vb, pa0, pa1, pa2, pa3);
	ds_write_b128 v181, v[250:253] offset:24576
	s_waitcnt lgkmcnt(10)
	v_mfma_f32_32x32x16_bf16 v[48:63], v[184:187], v[230:233], v[48:63]
	ds_read_b64_tr_b16 v[204:205], v182 offset:37888
	ds_read_b64_tr_b16 v[206:207], v182 offset:39936
	v_exp_f32_e32 v136, v136
	v_exp_f32_e32 v137, v137
	s_waitcnt lgkmcnt(10)
	v_mfma_f32_32x32x16_bf16 v[48:63], v[188:191], v[234:237], v[48:63]
	ds_read_b64_tr_b16 v[208:209], v182 offset:41984
	ds_read_b64_tr_b16 v[210:211], v182 offset:44032
	v_exp_f32_e32 v138, v138
	v_exp_f32_e32 v139, v139
	s_waitcnt vmcnt(1)
	ds_write_b128 v180, v[164:167] offset:0
	s_waitcnt lgkmcnt(11)
	v_mfma_f32_32x32x16_bf16 v[48:63], v[192:195], v[238:241], v[48:63]
	ds_read_b64_tr_b16 v[212:213], v182 offset:46080
	ds_read_b64_tr_b16 v[214:215], v182 offset:48128
	v_exp_f32_e32 v140, v140
	v_exp_f32_e32 v141, v141
	s_waitcnt lgkmcnt(10)
	v_mfma_f32_32x32x16_bf16 v[48:63], v[196:199], v[242:245], v[48:63]
	ds_read_b64_tr_b16 v[230:231], v182 offset:34304
	ds_read_b64_tr_b16 v[232:233], v182 offset:36352
	v_exp_f32_e32 v142, v142
	v_exp_f32_e32 v143, v143
	s_waitcnt vmcnt(0)
	ds_write_b128 v180, v[160:163] offset:8192
	s_waitcnt lgkmcnt(11)
	v_mfma_f32_32x32x16_bf16 v[32:47], v[184:187], v[200:203], v[32:47]
	ds_read_b64_tr_b16 v[234:235], v182 offset:38400
	ds_read_b64_tr_b16 v[236:237], v182 offset:40448
	ds_read_b128 v[200:203], v172 offset:0
	v_exp_f32_e32 v144, v144
	v_exp_f32_e32 v145, v145
	s_waitcnt lgkmcnt(11)
	v_mfma_f32_32x32x16_bf16 v[32:47], v[188:191], v[204:207], v[32:47]
	ds_read_b64_tr_b16 v[238:239], v182 offset:42496
	ds_read_b64_tr_b16 v[240:241], v182 offset:44544
	ds_read_b128 v[204:207], v172 offset:8192
	v_exp_f32_e32 v146, v146
	v_exp_f32_e32 v147, v147
	s_waitcnt lgkmcnt(12)
	v_mfma_f32_32x32x16_bf16 v[32:47], v[192:195], v[208:211], v[32:47]
	ds_read_b64_tr_b16 v[242:243], v182 offset:46592
	ds_read_b64_tr_b16 v[244:245], v182 offset:48640
	ds_read_b128 v[208:211], v173 offset:0
	v_exp_f32_e32 v148, v148
	v_exp_f32_e32 v149, v149
	s_waitcnt lgkmcnt(12)
	v_mfma_f32_32x32x16_bf16 v[32:47], v[196:199], v[212:215], v[32:47]
	ds_read_b128 v[212:215], v173 offset:8192
	v_exp_f32_e32 v150, v150
	v_exp_f32_e32 v151, v151
	s_waitcnt lgkmcnt(11)
	v_mfma_f32_32x32x16_bf16 v[16:31], v[184:187], v[230:233], v[16:31]
	ds_read_b128 v[230:233], v174 offset:0
	v_exp_f32_e32 v152, v152
	v_exp_f32_e32 v153, v153
	s_waitcnt lgkmcnt(9)
	v_mfma_f32_32x32x16_bf16 v[16:31], v[188:191], v[234:237], v[16:31]
	ds_read_b128 v[234:237], v174 offset:8192
	v_exp_f32_e32 v154, v154
	v_exp_f32_e32 v155, v155
	s_waitcnt lgkmcnt(7)
	v_mfma_f32_32x32x16_bf16 v[16:31], v[192:195], v[238:241], v[16:31]
	ds_read_b128 v[238:241], v175 offset:0
	v_exp_f32_e32 v156, v156
	v_exp_f32_e32 v157, v157
	s_waitcnt lgkmcnt(5)
	v_mfma_f32_32x32x16_bf16 v[16:31], v[196:199], v[242:245], v[16:31]
	ds_read_b128 v[242:245], v175 offset:8192
	v_exp_f32_e32 v158, v158
	v_exp_f32_e32 v159, v159
	s_barrier
	v_mfma_f32_32x32x16_bf16 v[64:79], v[200:203], v[124:127], 0
	ds_read_b128 v[200:203], v176 offset:0
	v_cvt_pk_bf16_f32 v184, v128, v129
	v_add_f32_e32 v169, v169, v128
	v_add_f32_e32 v219, v219, v129
	global_load_dwordx4 v[246:249], v183, s[98:99]
	v_mfma_f32_32x32x16_bf16 v[80:95], v[204:207], v[124:127], 0
	ds_read_b128 v[204:207], v176 offset:8192
	v_cvt_pk_bf16_f32 v185, v130, v131
	v_add_f32_e32 v222, v222, v130
	v_add_f32_e32 v254, v254, v131
	s_waitcnt lgkmcnt(7)
	v_mfma_f32_32x32x16_bf16 v[64:79], v[208:211], v[120:123], v[64:79]
	ds_read_b128 v[208:211], v177 offset:0
	v_cvt_pk_bf16_f32 v186, v132, v133
	v_add_f32_e32 v169, v169, v132
	v_add_f32_e32 v219, v219, v133
	global_load_dwordx4 v[250:253], v183, s[100:101]
	s_add_u32 s98, s98, 0x150000
	s_addc_u32 s99, s99, 0
	s_add_u32 s100, s100, 0x150000
	s_addc_u32 s101, s101, 0
	s_waitcnt lgkmcnt(7)
	v_mfma_f32_32x32x16_bf16 v[80:95], v[212:215], v[120:123], v[80:95]
	ds_read_b128 v[212:215], v177 offset:8192
	v_cvt_pk_bf16_f32 v187, v134, v135
	v_add_f32_e32 v222, v222, v134
	v_add_f32_e32 v254, v254, v135
	s_waitcnt lgkmcnt(7)
	v_mfma_f32_32x32x16_bf16 v[64:79], v[230:233], v[116:119], v[64:79]
	ds_read_b128 v[230:233], v178 offset:0
	v_cvt_pk_bf16_f32 v188, v136, v137
	v_add_f32_e32 v169, v169, v136
	v_add_f32_e32 v219, v219, v137
	v_permlane32_swap_b32_e32 v184, v186
	global_load_dwordx4 v[164:167], v183, s[0:1] offset:512
	s_waitcnt lgkmcnt(7)
	v_mfma_f32_32x32x16_bf16 v[80:95], v[234:237], v[116:119], v[80:95]
	ds_read_b128 v[234:237], v178 offset:8192
	v_cvt_pk_bf16_f32 v189, v138, v139
	v_add_f32_e32 v222, v222, v138
	v_add_f32_e32 v254, v254, v139
	v_permlane32_swap_b32_e32 v185, v187
	s_waitcnt lgkmcnt(7)
	v_mfma_f32_32x32x16_bf16 v[64:79], v[238:241], v[112:115], v[64:79]
	ds_read_b128 v[238:241], v179 offset:0
	v_cvt_pk_bf16_f32 v190, v140, v141
	v_add_f32_e32 v169, v169, v140
	v_add_f32_e32 v219, v219, v141
	global_load_dwordx4 v[160:163], v183, s[4:5] offset:512
	s_add_u32 s0, s0, 0x150000
	s_addc_u32 s1, s1, 0
	s_add_u32 s4, s4, 0x150000
	s_addc_u32 s5, s5, 0
	s_waitcnt lgkmcnt(7)
	v_mfma_f32_32x32x16_bf16 v[80:95], v[242:245], v[112:115], v[80:95]
	ds_read_b128 v[242:245], v179 offset:8192
	v_cvt_pk_bf16_f32 v191, v142, v143
	v_add_f32_e32 v222, v222, v142
	v_add_f32_e32 v254, v254, v143
	s_waitcnt lgkmcnt(7)
	v_mfma_f32_32x32x16_bf16 v[64:79], v[200:203], v[108:111], v[64:79]
	v_cvt_pk_bf16_f32 v192, v144, v145
	v_add_f32_e32 v169, v169, v144
	v_add_f32_e32 v219, v219, v145
	v_permlane32_swap_b32_e32 v188, v190
	s_waitcnt lgkmcnt(6)
	v_mfma_f32_32x32x16_bf16 v[80:95], v[204:207], v[108:111], v[80:95]
	v_cvt_pk_bf16_f32 v193, v146, v147
	v_add_f32_e32 v222, v222, v146
	v_add_f32_e32 v254, v254, v147
	v_permlane32_swap_b32_e32 v189, v191
	s_waitcnt lgkmcnt(5)
	v_mfma_f32_32x32x16_bf16 v[64:79], v[208:211], v[104:107], v[64:79]
	v_cvt_pk_bf16_f32 v194, v148, v149
	v_add_f32_e32 v169, v169, v148
	v_add_f32_e32 v219, v219, v149
	s_waitcnt lgkmcnt(4)
	v_mfma_f32_32x32x16_bf16 v[80:95], v[212:215], v[104:107], v[80:95]
	ds_read_b64_tr_b16 v[200:201], v182 offset:49152
	ds_read_b64_tr_b16 v[202:203], v182 offset:51200
	v_cvt_pk_bf16_f32 v195, v150, v151
	v_add_f32_e32 v222, v222, v150
	v_add_f32_e32 v254, v254, v151
	s_waitcnt lgkmcnt(5)
	v_mfma_f32_32x32x16_bf16 v[64:79], v[230:233], v[100:103], v[64:79]
	ds_read_b64_tr_b16 v[204:205], v182 offset:53248
	ds_read_b64_tr_b16 v[206:207], v182 offset:55296
	v_cvt_pk_bf16_f32 v196, v152, v153
	v_add_f32_e32 v169, v169, v152
	v_add_f32_e32 v219, v219, v153
	v_permlane32_swap_b32_e32 v192, v194
	s_waitcnt lgkmcnt(6)
	v_mfma_f32_32x32x16_bf16 v[80:95], v[234:237], v[100:103], v[80:95]
	ds_read_b64_tr_b16 v[208:209], v182 offset:57344
	ds_read_b64_tr_b16 v[210:211], v182 offset:59392
	v_cvt_pk_bf16_f32 v197, v154, v155
	v_add_f32_e32 v222, v222, v154
	v_add_f32_e32 v254, v254, v155
	v_permlane32_swap_b32_e32 v193, v195
	s_waitcnt lgkmcnt(7)
	v_mfma_f32_32x32x16_bf16 v[64:79], v[238:241], v[96:99], v[64:79]
	ds_read_b64_tr_b16 v[212:213], v182 offset:61440
	ds_read_b64_tr_b16 v[214:215], v182 offset:63488
	v_cvt_pk_bf16_f32 v198, v156, v157
	v_add_f32_e32 v169, v169, v156
	v_add_f32_e32 v219, v219, v157
	s_waitcnt lgkmcnt(8)
	v_mfma_f32_32x32x16_bf16 v[80:95], v[242:245], v[96:99], v[80:95]
	ds_read_b64_tr_b16 v[230:231], v182 offset:49664
	ds_read_b64_tr_b16 v[232:233], v182 offset:51712
	v_cvt_pk_bf16_f32 v199, v158, v159
	v_add_f32_e32 v222, v222, v158
	v_add_f32_e32 v254, v254, v159
	v_permlane32_swap_b32_e32 v196, v198
	v_permlane32_swap_b32_e32 v197, v199
	s_waitcnt lgkmcnt(8)
	v_mfma_f32_32x32x16_bf16 v[0:15], v[184:187], v[200:203], v[0:15]
	ds_read_b64_tr_b16 v[234:235], v182 offset:53760
	ds_read_b64_tr_b16 v[236:237], v182 offset:55808
	v_exp_f32_e32 v64, v64
	v_exp_f32_e32 v65, v65
	s_waitcnt lgkmcnt(8)
	v_mfma_f32_32x32x16_bf16 v[0:15], v[188:191], v[204:207], v[0:15]
	ds_read_b64_tr_b16 v[238:239], v182 offset:57856
	ds_read_b64_tr_b16 v[240:241], v182 offset:59904
	v_exp_f32_e32 v66, v66
	v_exp_f32_e32 v67, v67
	s_waitcnt vmcnt(3)
	ds_write_b128 v181, v[246:249] offset:32768
	s_waitcnt lgkmcnt(9)
	v_mfma_f32_32x32x16_bf16 v[0:15], v[192:195], v[208:211], v[0:15]
	ds_read_b64_tr_b16 v[242:243], v182 offset:61952
	ds_read_b64_tr_b16 v[244:245], v182 offset:64000
	v_exp_f32_e32 v68, v68
	v_exp_f32_e32 v69, v69
	s_waitcnt lgkmcnt(9)
	v_mfma_f32_32x32x16_bf16 v[0:15], v[196:199], v[212:215], v[0:15]
	ds_read_b64_tr_b16 v[200:201], v182 offset:50176
	ds_read_b64_tr_b16 v[202:203], v182 offset:52224
	v_exp_f32_e32 v70, v70
	v_exp_f32_e32 v71, v71
	s_waitcnt vmcnt(2)
	ds_write_b128 v181, v[250:253] offset:40960
	s_waitcnt lgkmcnt(10)
	v_mfma_f32_32x32x16_bf16 v[48:63], v[184:187], v[230:233], v[48:63]
	ds_read_b64_tr_b16 v[204:205], v182 offset:54272
	ds_read_b64_tr_b16 v[206:207], v182 offset:56320
	v_exp_f32_e32 v72, v72
	v_exp_f32_e32 v73, v73
	s_waitcnt lgkmcnt(10)
	v_mfma_f32_32x32x16_bf16 v[48:63], v[188:191], v[234:237], v[48:63]
	ds_read_b64_tr_b16 v[208:209], v182 offset:58368
	ds_read_b64_tr_b16 v[210:211], v182 offset:60416
	v_exp_f32_e32 v74, v74
	v_exp_f32_e32 v75, v75
	s_waitcnt vmcnt(1)
	ds_write_b128 v180, v[164:167] offset:16384
	s_waitcnt lgkmcnt(11)
	v_mfma_f32_32x32x16_bf16 v[48:63], v[192:195], v[238:241], v[48:63]
	ds_read_b64_tr_b16 v[212:213], v182 offset:62464
	ds_read_b64_tr_b16 v[214:215], v182 offset:64512
	v_exp_f32_e32 v76, v76
	v_exp_f32_e32 v77, v77
	s_waitcnt lgkmcnt(10)
	v_mfma_f32_32x32x16_bf16 v[48:63], v[196:199], v[242:245], v[48:63]
	ds_read_b64_tr_b16 v[230:231], v182 offset:50688
	ds_read_b64_tr_b16 v[232:233], v182 offset:52736
	v_exp_f32_e32 v78, v78
	v_exp_f32_e32 v79, v79
	s_waitcnt vmcnt(0)
	ds_write_b128 v180, v[160:163] offset:24576
	s_waitcnt lgkmcnt(11)
	v_mfma_f32_32x32x16_bf16 v[32:47], v[184:187], v[200:203], v[32:47]
	ds_read_b64_tr_b16 v[234:235], v182 offset:54784
	ds_read_b64_tr_b16 v[236:237], v182 offset:56832
	ds_read_b128 v[200:203], v172 offset:16384
	v_exp_f32_e32 v80, v80
	v_exp_f32_e32 v81, v81
	s_waitcnt lgkmcnt(11)
	v_mfma_f32_32x32x16_bf16 v[32:47], v[188:191], v[204:207], v[32:47]
	ds_read_b64_tr_b16 v[238:239], v182 offset:58880
	ds_read_b64_tr_b16 v[240:241], v182 offset:60928
	ds_read_b128 v[204:207], v172 offset:24576
	v_exp_f32_e32 v82, v82
	v_exp_f32_e32 v83, v83
	s_waitcnt lgkmcnt(12)
	v_mfma_f32_32x32x16_bf16 v[32:47], v[192:195], v[208:211], v[32:47]
	ds_read_b64_tr_b16 v[242:243], v182 offset:62976
	ds_read_b64_tr_b16 v[244:245], v182 offset:65024
	ds_read_b128 v[208:211], v173 offset:16384
	v_exp_f32_e32 v84, v84
	v_exp_f32_e32 v85, v85
	s_waitcnt lgkmcnt(12)
	v_mfma_f32_32x32x16_bf16 v[32:47], v[196:199], v[212:215], v[32:47]
	ds_read_b128 v[212:215], v173 offset:24576
	v_exp_f32_e32 v86, v86
	v_exp_f32_e32 v87, v87
	s_waitcnt lgkmcnt(11)
	v_mfma_f32_32x32x16_bf16 v[16:31], v[184:187], v[230:233], v[16:31]
	ds_read_b128 v[230:233], v174 offset:16384
	v_exp_f32_e32 v88, v88
	v_exp_f32_e32 v89, v89
	s_waitcnt lgkmcnt(9)
	v_mfma_f32_32x32x16_bf16 v[16:31], v[188:191], v[234:237], v[16:31]
	ds_read_b128 v[234:237], v174 offset:24576
	v_exp_f32_e32 v90, v90
	v_exp_f32_e32 v91, v91
	s_waitcnt lgkmcnt(7)
	v_mfma_f32_32x32x16_bf16 v[16:31], v[192:195], v[238:241], v[16:31]
	ds_read_b128 v[238:241], v175 offset:16384
	v_exp_f32_e32 v92, v92
	v_exp_f32_e32 v93, v93
	s_waitcnt lgkmcnt(5)
	v_mfma_f32_32x32x16_bf16 v[16:31], v[196:199], v[242:245], v[16:31]
	ds_read_b128 v[242:245], v175 offset:24576
	v_exp_f32_e32 v94, v94
	v_exp_f32_e32 v95, v95
	s_barrier
;     ...
;   for (int p = 0; p + 2 < NP; p += 2) {
;     PAIR_FULL(0, 1, p + 1);
;     PAIR_FULL(1, 0, p + 2);
;   }
;   PAIR_FULL(0, 1, NP - 1);
	s_add_i32 s44, s44, 1
	s_cmp_lt_u32 s44, 63
	s_cbranch_scc1 .Ldense_loop
	v_mfma_f32_32x32x16_bf16 v[128:143], v[200:203], v[124:127], 0
	ds_read_b128 v[200:203], v176 offset:16384
	v_cvt_pk_bf16_f32 v184, v64, v65
	v_add_f32_e32 v169, v169, v64
	v_add_f32_e32 v219, v219, v65
	global_load_dwordx4 v[246:249], v183, s[98:99]
	v_mfma_f32_32x32x16_bf16 v[144:159], v[204:207], v[124:127], 0
	ds_read_b128 v[204:207], v176 offset:24576
	v_cvt_pk_bf16_f32 v185, v66, v67
	v_add_f32_e32 v222, v222, v66
	v_add_f32_e32 v254, v254, v67
	s_waitcnt lgkmcnt(7)
	v_mfma_f32_32x32x16_bf16 v[128:143], v[208:211], v[120:123], v[128:143]
	ds_read_b128 v[208:211], v177 offset:16384
	v_cvt_pk_bf16_f32 v186, v68, v69
	v_add_f32_e32 v169, v169, v68
	v_add_f32_e32 v219, v219, v69
	global_load_dwordx4 v[250:253], v183, s[100:101]
	s_add_u32 s98, s98, 0x150000
	s_addc_u32 s99, s99, 0
	s_add_u32 s100, s100, 0x150000
	s_addc_u32 s101, s101, 0
	s_waitcnt lgkmcnt(7)
	v_mfma_f32_32x32x16_bf16 v[144:159], v[212:215], v[120:123], v[144:159]
	ds_read_b128 v[212:215], v177 offset:24576
	v_cvt_pk_bf16_f32 v187, v70, v71
	v_add_f32_e32 v222, v222, v70
	v_add_f32_e32 v254, v254, v71
	s_waitcnt lgkmcnt(7)
	v_mfma_f32_32x32x16_bf16 v[128:143], v[230:233], v[116:119], v[128:143]
	ds_read_b128 v[230:233], v178 offset:16384
	v_cvt_pk_bf16_f32 v188, v72, v73
	v_add_f32_e32 v169, v169, v72
	v_add_f32_e32 v219, v219, v73
	v_permlane32_swap_b32_e32 v184, v186
	global_load_dwordx4 v[164:167], v183, s[0:1] offset:512
	s_waitcnt lgkmcnt(7)
	v_mfma_f32_32x32x16_bf16 v[144:159], v[234:237], v[116:119], v[144:159]
	ds_read_b128 v[234:237], v178 offset:24576
	v_cvt_pk_bf16_f32 v189, v74, v75
	v_add_f32_e32 v222, v222, v74
	v_add_f32_e32 v254, v254, v75
	v_permlane32_swap_b32_e32 v185, v187
	s_waitcnt lgkmcnt(7)
	v_mfma_f32_32x32x16_bf16 v[128:143], v[238:241], v[112:115], v[128:143]
	ds_read_b128 v[238:241], v179 offset:16384
	v_cvt_pk_bf16_f32 v190, v76, v77
	v_add_f32_e32 v169, v169, v76
	v_add_f32_e32 v219, v219, v77
	global_load_dwordx4 v[160:163], v183, s[4:5] offset:512
	s_add_u32 s0, s0, 0x150000
	s_addc_u32 s1, s1, 0
	s_add_u32 s4, s4, 0x150000
	s_addc_u32 s5, s5, 0
	s_waitcnt lgkmcnt(7)
	v_mfma_f32_32x32x16_bf16 v[144:159], v[242:245], v[112:115], v[144:159]
	ds_read_b128 v[242:245], v179 offset:24576
	v_cvt_pk_bf16_f32 v191, v78, v79
	v_add_f32_e32 v222, v222, v78
	v_add_f32_e32 v254, v254, v79
	s_waitcnt lgkmcnt(7)
	v_mfma_f32_32x32x16_bf16 v[128:143], v[200:203], v[108:111], v[128:143]
	v_cvt_pk_bf16_f32 v192, v80, v81
	v_add_f32_e32 v169, v169, v80
	v_add_f32_e32 v219, v219, v81
	v_permlane32_swap_b32_e32 v188, v190
	s_waitcnt lgkmcnt(6)
	v_mfma_f32_32x32x16_bf16 v[144:159], v[204:207], v[108:111], v[144:159]
	v_cvt_pk_bf16_f32 v193, v82, v83
	v_add_f32_e32 v222, v222, v82
	v_add_f32_e32 v254, v254, v83
	v_permlane32_swap_b32_e32 v189, v191
	s_waitcnt lgkmcnt(5)
	v_mfma_f32_32x32x16_bf16 v[128:143], v[208:211], v[104:107], v[128:143]
	v_cvt_pk_bf16_f32 v194, v84, v85
	v_add_f32_e32 v169, v169, v84
	v_add_f32_e32 v219, v219, v85
	s_waitcnt lgkmcnt(4)
	v_mfma_f32_32x32x16_bf16 v[144:159], v[212:215], v[104:107], v[144:159]
	ds_read_b64_tr_b16 v[200:201], v182 offset:0
	ds_read_b64_tr_b16 v[202:203], v182 offset:2048
	v_cvt_pk_bf16_f32 v195, v86, v87
	v_add_f32_e32 v222, v222, v86
	v_add_f32_e32 v254, v254, v87
	s_waitcnt lgkmcnt(5)
	v_mfma_f32_32x32x16_bf16 v[128:143], v[230:233], v[100:103], v[128:143]
	ds_read_b64_tr_b16 v[204:205], v182 offset:4096
	ds_read_b64_tr_b16 v[206:207], v182 offset:6144
	v_cvt_pk_bf16_f32 v196, v88, v89
	v_add_f32_e32 v169, v169, v88
	v_add_f32_e32 v219, v219, v89
	v_permlane32_swap_b32_e32 v192, v194
	s_waitcnt lgkmcnt(6)
	v_mfma_f32_32x32x16_bf16 v[144:159], v[234:237], v[100:103], v[144:159]
	ds_read_b64_tr_b16 v[208:209], v182 offset:8192
	ds_read_b64_tr_b16 v[210:211], v182 offset:10240
	v_cvt_pk_bf16_f32 v197, v90, v91
	v_add_f32_e32 v222, v222, v90
	v_add_f32_e32 v254, v254, v91
	v_permlane32_swap_b32_e32 v193, v195
	s_waitcnt lgkmcnt(7)
	v_mfma_f32_32x32x16_bf16 v[128:143], v[238:241], v[96:99], v[128:143]
	ds_read_b64_tr_b16 v[212:213], v182 offset:12288
	ds_read_b64_tr_b16 v[214:215], v182 offset:14336
	v_cvt_pk_bf16_f32 v198, v92, v93
	v_add_f32_e32 v169, v169, v92
	v_add_f32_e32 v219, v219, v93
	s_waitcnt lgkmcnt(8)
	v_mfma_f32_32x32x16_bf16 v[144:159], v[242:245], v[96:99], v[144:159]
	ds_read_b64_tr_b16 v[230:231], v182 offset:512
	ds_read_b64_tr_b16 v[232:233], v182 offset:2560
	v_cvt_pk_bf16_f32 v199, v94, v95
	v_add_f32_e32 v222, v222, v94
	v_add_f32_e32 v254, v254, v95
	v_permlane32_swap_b32_e32 v196, v198
	v_permlane32_swap_b32_e32 v197, v199
	s_waitcnt lgkmcnt(8)
	v_mfma_f32_32x32x16_bf16 v[0:15], v[184:187], v[200:203], v[0:15]
	ds_read_b64_tr_b16 v[234:235], v182 offset:4608
	ds_read_b64_tr_b16 v[236:237], v182 offset:6656
	v_exp_f32_e32 v128, v128
	v_exp_f32_e32 v129, v129
	s_waitcnt lgkmcnt(8)
	v_mfma_f32_32x32x16_bf16 v[0:15], v[188:191], v[204:207], v[0:15]
	ds_read_b64_tr_b16 v[238:239], v182 offset:8704
	ds_read_b64_tr_b16 v[240:241], v182 offset:10752
	v_exp_f32_e32 v130, v130
	v_exp_f32_e32 v131, v131
	s_waitcnt vmcnt(3)
	ds_write_b128 v181, v[246:249] offset:49152
	s_waitcnt lgkmcnt(9)
	v_mfma_f32_32x32x16_bf16 v[0:15], v[192:195], v[208:211], v[0:15]
	ds_read_b64_tr_b16 v[242:243], v182 offset:12800
	ds_read_b64_tr_b16 v[244:245], v182 offset:14848
	v_exp_f32_e32 v132, v132
	v_exp_f32_e32 v133, v133
	s_waitcnt lgkmcnt(9)
	v_mfma_f32_32x32x16_bf16 v[0:15], v[196:199], v[212:215], v[0:15]
	ds_read_b64_tr_b16 v[200:201], v182 offset:1024
	ds_read_b64_tr_b16 v[202:203], v182 offset:3072
	v_exp_f32_e32 v134, v134
	v_exp_f32_e32 v135, v135
	s_waitcnt vmcnt(2)
	ds_write_b128 v181, v[250:253] offset:57344
	s_waitcnt lgkmcnt(10)
	v_mfma_f32_32x32x16_bf16 v[48:63], v[184:187], v[230:233], v[48:63]
	ds_read_b64_tr_b16 v[204:205], v182 offset:5120
	ds_read_b64_tr_b16 v[206:207], v182 offset:7168
	v_exp_f32_e32 v136, v136
	v_exp_f32_e32 v137, v137
	s_waitcnt lgkmcnt(10)
	v_mfma_f32_32x32x16_bf16 v[48:63], v[188:191], v[234:237], v[48:63]
	ds_read_b64_tr_b16 v[208:209], v182 offset:9216
	ds_read_b64_tr_b16 v[210:211], v182 offset:11264
	v_exp_f32_e32 v138, v138
	v_exp_f32_e32 v139, v139
	s_waitcnt vmcnt(1)
	ds_write_b128 v180, v[164:167] offset:32768
	s_waitcnt lgkmcnt(11)
	v_mfma_f32_32x32x16_bf16 v[48:63], v[192:195], v[238:241], v[48:63]
	ds_read_b64_tr_b16 v[212:213], v182 offset:13312
	ds_read_b64_tr_b16 v[214:215], v182 offset:15360
	v_exp_f32_e32 v140, v140
	v_exp_f32_e32 v141, v141
	s_waitcnt lgkmcnt(10)
	v_mfma_f32_32x32x16_bf16 v[48:63], v[196:199], v[242:245], v[48:63]
	ds_read_b64_tr_b16 v[230:231], v182 offset:1536
	ds_read_b64_tr_b16 v[232:233], v182 offset:3584
	v_exp_f32_e32 v142, v142
	v_exp_f32_e32 v143, v143
	s_waitcnt vmcnt(0)
	ds_write_b128 v180, v[160:163] offset:40960
	s_waitcnt lgkmcnt(11)
	v_mfma_f32_32x32x16_bf16 v[32:47], v[184:187], v[200:203], v[32:47]
	ds_read_b64_tr_b16 v[234:235], v182 offset:5632
	ds_read_b64_tr_b16 v[236:237], v182 offset:7680
	ds_read_b128 v[200:203], v172 offset:32768
	v_exp_f32_e32 v144, v144
	v_exp_f32_e32 v145, v145
	s_waitcnt lgkmcnt(11)
	v_mfma_f32_32x32x16_bf16 v[32:47], v[188:191], v[204:207], v[32:47]
	ds_read_b64_tr_b16 v[238:239], v182 offset:9728
	ds_read_b64_tr_b16 v[240:241], v182 offset:11776
	ds_read_b128 v[204:207], v172 offset:40960
	v_exp_f32_e32 v146, v146
	v_exp_f32_e32 v147, v147
	s_waitcnt lgkmcnt(12)
	v_mfma_f32_32x32x16_bf16 v[32:47], v[192:195], v[208:211], v[32:47]
	ds_read_b64_tr_b16 v[242:243], v182 offset:13824
	ds_read_b64_tr_b16 v[244:245], v182 offset:15872
	ds_read_b128 v[208:211], v173 offset:32768
	v_exp_f32_e32 v148, v148
	v_exp_f32_e32 v149, v149
	s_waitcnt lgkmcnt(12)
	v_mfma_f32_32x32x16_bf16 v[32:47], v[196:199], v[212:215], v[32:47]
	ds_read_b128 v[212:215], v173 offset:40960
	v_exp_f32_e32 v150, v150
	v_exp_f32_e32 v151, v151
	s_waitcnt lgkmcnt(11)
	v_mfma_f32_32x32x16_bf16 v[16:31], v[184:187], v[230:233], v[16:31]
	ds_read_b128 v[230:233], v174 offset:32768
	v_exp_f32_e32 v152, v152
	v_exp_f32_e32 v153, v153
	s_waitcnt lgkmcnt(9)
	v_mfma_f32_32x32x16_bf16 v[16:31], v[188:191], v[234:237], v[16:31]
	ds_read_b128 v[234:237], v174 offset:40960
	v_exp_f32_e32 v154, v154
	v_exp_f32_e32 v155, v155
	s_waitcnt lgkmcnt(7)
	v_mfma_f32_32x32x16_bf16 v[16:31], v[192:195], v[238:241], v[16:31]
	ds_read_b128 v[238:241], v175 offset:32768
	v_exp_f32_e32 v156, v156
	v_exp_f32_e32 v157, v157
	s_waitcnt lgkmcnt(5)
	v_mfma_f32_32x32x16_bf16 v[16:31], v[196:199], v[242:245], v[16:31]
	ds_read_b128 v[242:245], v175 offset:40960
	v_exp_f32_e32 v158, v158
	v_exp_f32_e32 v159, v159
	s_barrier
	v_mfma_f32_32x32x16_bf16 v[64:79], v[200:203], v[124:127], 0
	ds_read_b128 v[200:203], v176 offset:32768
	v_cvt_pk_bf16_f32 v184, v128, v129
	v_add_f32_e32 v169, v169, v128
	v_add_f32_e32 v219, v219, v129
	global_load_dwordx4 v[164:167], v183, s[0:1] offset:512
	v_mfma_f32_32x32x16_bf16 v[80:95], v[204:207], v[124:127], 0
	ds_read_b128 v[204:207], v176 offset:40960
	v_cvt_pk_bf16_f32 v185, v130, v131
	v_add_f32_e32 v222, v222, v130
	v_add_f32_e32 v254, v254, v131
	s_waitcnt lgkmcnt(7)
	v_mfma_f32_32x32x16_bf16 v[64:79], v[208:211], v[120:123], v[64:79]
	ds_read_b128 v[208:211], v177 offset:32768
	v_cvt_pk_bf16_f32 v186, v132, v133
	v_add_f32_e32 v169, v169, v132
	v_add_f32_e32 v219, v219, v133
	global_load_dwordx4 v[160:163], v183, s[4:5] offset:512
	s_add_u32 s0, s0, 0x150000
	s_addc_u32 s1, s1, 0
	s_add_u32 s4, s4, 0x150000
	s_addc_u32 s5, s5, 0
	s_waitcnt lgkmcnt(7)
	v_mfma_f32_32x32x16_bf16 v[80:95], v[212:215], v[120:123], v[80:95]
	ds_read_b128 v[212:215], v177 offset:40960
	v_cvt_pk_bf16_f32 v187, v134, v135
	v_add_f32_e32 v222, v222, v134
	v_add_f32_e32 v254, v254, v135
	s_waitcnt lgkmcnt(7)
	v_mfma_f32_32x32x16_bf16 v[64:79], v[230:233], v[116:119], v[64:79]
	ds_read_b128 v[230:233], v178 offset:32768
	v_cvt_pk_bf16_f32 v188, v136, v137
	v_add_f32_e32 v169, v169, v136
	v_add_f32_e32 v219, v219, v137
	v_permlane32_swap_b32_e32 v184, v186
	s_waitcnt lgkmcnt(7)
	v_mfma_f32_32x32x16_bf16 v[80:95], v[234:237], v[116:119], v[80:95]
	ds_read_b128 v[234:237], v178 offset:40960
	v_cvt_pk_bf16_f32 v189, v138, v139
	v_add_f32_e32 v222, v222, v138
	v_add_f32_e32 v254, v254, v139
	v_permlane32_swap_b32_e32 v185, v187
	s_waitcnt lgkmcnt(7)
	v_mfma_f32_32x32x16_bf16 v[64:79], v[238:241], v[112:115], v[64:79]
	ds_read_b128 v[238:241], v179 offset:32768
	v_cvt_pk_bf16_f32 v190, v140, v141
	v_add_f32_e32 v169, v169, v140
	v_add_f32_e32 v219, v219, v141
	s_waitcnt lgkmcnt(7)
	v_mfma_f32_32x32x16_bf16 v[80:95], v[242:245], v[112:115], v[80:95]
	ds_read_b128 v[242:245], v179 offset:40960
	v_cvt_pk_bf16_f32 v191, v142, v143
	v_add_f32_e32 v222, v222, v142
	v_add_f32_e32 v254, v254, v143
	s_waitcnt lgkmcnt(7)
	v_mfma_f32_32x32x16_bf16 v[64:79], v[200:203], v[108:111], v[64:79]
	v_cvt_pk_bf16_f32 v192, v144, v145
	v_add_f32_e32 v169, v169, v144
	v_add_f32_e32 v219, v219, v145
	v_permlane32_swap_b32_e32 v188, v190
	s_waitcnt lgkmcnt(6)
	v_mfma_f32_32x32x16_bf16 v[80:95], v[204:207], v[108:111], v[80:95]
	v_cvt_pk_bf16_f32 v193, v146, v147
	v_add_f32_e32 v222, v222, v146
	v_add_f32_e32 v254, v254, v147
	v_permlane32_swap_b32_e32 v189, v191
	s_waitcnt lgkmcnt(5)
; #define SBAR() __builtin_amdgcn_sched_barrier(0)
;     ...
;   { SBAR(); qkt(pB0, pB1, KSUB(1, 1), qr, r32, hi);
	v_mfma_f32_32x32x16_bf16 v[64:79], v[208:211], v[104:107], v[64:79]
	v_cvt_pk_bf16_f32 v194, v148, v149
	v_add_f32_e32 v169, v169, v148
	v_add_f32_e32 v219, v219, v149
	s_waitcnt lgkmcnt(4)
	v_mfma_f32_32x32x16_bf16 v[80:95], v[212:215], v[104:107], v[80:95]
	ds_read_b64_tr_b16 v[200:201], v182 offset:16384
	ds_read_b64_tr_b16 v[202:203], v182 offset:18432
	v_cvt_pk_bf16_f32 v195, v150, v151
	v_add_f32_e32 v222, v222, v150
	v_add_f32_e32 v254, v254, v151
	s_waitcnt lgkmcnt(5)
	v_mfma_f32_32x32x16_bf16 v[64:79], v[230:233], v[100:103], v[64:79]
	ds_read_b64_tr_b16 v[204:205], v182 offset:20480
	ds_read_b64_tr_b16 v[206:207], v182 offset:22528
	v_cvt_pk_bf16_f32 v196, v152, v153
	v_add_f32_e32 v169, v169, v152
	v_add_f32_e32 v219, v219, v153
	v_permlane32_swap_b32_e32 v192, v194
	s_waitcnt lgkmcnt(6)
	v_mfma_f32_32x32x16_bf16 v[80:95], v[234:237], v[100:103], v[80:95]
	ds_read_b64_tr_b16 v[208:209], v182 offset:24576
	ds_read_b64_tr_b16 v[210:211], v182 offset:26624
	v_cvt_pk_bf16_f32 v197, v154, v155
	v_add_f32_e32 v222, v222, v154
	v_add_f32_e32 v254, v254, v155
	v_permlane32_swap_b32_e32 v193, v195
	s_waitcnt lgkmcnt(7)
	v_mfma_f32_32x32x16_bf16 v[64:79], v[238:241], v[96:99], v[64:79]
	ds_read_b64_tr_b16 v[212:213], v182 offset:28672
	ds_read_b64_tr_b16 v[214:215], v182 offset:30720
	v_cvt_pk_bf16_f32 v198, v156, v157
	v_add_f32_e32 v169, v169, v156
	v_add_f32_e32 v219, v219, v157
	s_waitcnt lgkmcnt(8)
	v_mfma_f32_32x32x16_bf16 v[80:95], v[242:245], v[96:99], v[80:95]
	ds_read_b64_tr_b16 v[230:231], v182 offset:16896
	ds_read_b64_tr_b16 v[232:233], v182 offset:18944
	v_cvt_pk_bf16_f32 v199, v158, v159
	v_add_f32_e32 v222, v222, v158
	v_add_f32_e32 v254, v254, v159
	v_permlane32_swap_b32_e32 v196, v198
	v_permlane32_swap_b32_e32 v197, v199
	s_waitcnt lgkmcnt(8)
	v_mfma_f32_32x32x16_bf16 v[0:15], v[184:187], v[200:203], v[0:15]
	ds_read_b64_tr_b16 v[234:235], v182 offset:20992
	ds_read_b64_tr_b16 v[236:237], v182 offset:23040
	v_exp_f32_e32 v64, v64
	v_exp_f32_e32 v65, v65
	s_waitcnt lgkmcnt(8)
	v_mfma_f32_32x32x16_bf16 v[0:15], v[188:191], v[204:207], v[0:15]
	ds_read_b64_tr_b16 v[238:239], v182 offset:25088
	ds_read_b64_tr_b16 v[240:241], v182 offset:27136
	v_exp_f32_e32 v66, v66
	v_exp_f32_e32 v67, v67
	s_waitcnt vmcnt(1)
	ds_write_b128 v180, v[164:167] offset:49152
	s_waitcnt lgkmcnt(9)
	v_mfma_f32_32x32x16_bf16 v[0:15], v[192:195], v[208:211], v[0:15]
	ds_read_b64_tr_b16 v[242:243], v182 offset:29184
	ds_read_b64_tr_b16 v[244:245], v182 offset:31232
	v_exp_f32_e32 v68, v68
	v_exp_f32_e32 v69, v69
	s_waitcnt lgkmcnt(9)
	v_mfma_f32_32x32x16_bf16 v[0:15], v[196:199], v[212:215], v[0:15]
	ds_read_b64_tr_b16 v[200:201], v182 offset:17408
	ds_read_b64_tr_b16 v[202:203], v182 offset:19456
	v_exp_f32_e32 v70, v70
	v_exp_f32_e32 v71, v71
	s_waitcnt vmcnt(0)
	ds_write_b128 v180, v[160:163] offset:57344
	s_waitcnt lgkmcnt(10)
	v_mfma_f32_32x32x16_bf16 v[48:63], v[184:187], v[230:233], v[48:63]
	ds_read_b64_tr_b16 v[204:205], v182 offset:21504
	ds_read_b64_tr_b16 v[206:207], v182 offset:23552
	v_exp_f32_e32 v72, v72
	v_exp_f32_e32 v73, v73
	s_waitcnt lgkmcnt(10)
	v_mfma_f32_32x32x16_bf16 v[48:63], v[188:191], v[234:237], v[48:63]
	ds_read_b64_tr_b16 v[208:209], v182 offset:25600
	ds_read_b64_tr_b16 v[210:211], v182 offset:27648
	v_exp_f32_e32 v74, v74
	v_exp_f32_e32 v75, v75
	s_waitcnt lgkmcnt(10)
	v_mfma_f32_32x32x16_bf16 v[48:63], v[192:195], v[238:241], v[48:63]
	ds_read_b64_tr_b16 v[212:213], v182 offset:29696
	ds_read_b64_tr_b16 v[214:215], v182 offset:31744
	v_exp_f32_e32 v76, v76
	v_exp_f32_e32 v77, v77
	s_waitcnt lgkmcnt(9)
	v_mfma_f32_32x32x16_bf16 v[48:63], v[196:199], v[242:245], v[48:63]
	ds_read_b64_tr_b16 v[230:231], v182 offset:17920
	ds_read_b64_tr_b16 v[232:233], v182 offset:19968
	v_exp_f32_e32 v78, v78
	v_exp_f32_e32 v79, v79
	s_waitcnt lgkmcnt(9)
	v_mfma_f32_32x32x16_bf16 v[32:47], v[184:187], v[200:203], v[32:47]
	ds_read_b64_tr_b16 v[234:235], v182 offset:22016
	ds_read_b64_tr_b16 v[236:237], v182 offset:24064
	ds_read_b128 v[200:203], v172 offset:49152
	v_exp_f32_e32 v80, v80
	v_exp_f32_e32 v81, v81
	s_waitcnt lgkmcnt(9)
	v_mfma_f32_32x32x16_bf16 v[32:47], v[188:191], v[204:207], v[32:47]
	ds_read_b64_tr_b16 v[238:239], v182 offset:26112
	ds_read_b64_tr_b16 v[240:241], v182 offset:28160
	ds_read_b128 v[204:207], v172 offset:57344
	v_exp_f32_e32 v82, v82
	v_exp_f32_e32 v83, v83
	s_waitcnt lgkmcnt(10)
	v_mfma_f32_32x32x16_bf16 v[32:47], v[192:195], v[208:211], v[32:47]
	ds_read_b64_tr_b16 v[242:243], v182 offset:30208
	ds_read_b64_tr_b16 v[244:245], v182 offset:32256
	ds_read_b128 v[208:211], v173 offset:49152
	v_exp_f32_e32 v84, v84
	v_exp_f32_e32 v85, v85
	s_waitcnt lgkmcnt(11)
	v_mfma_f32_32x32x16_bf16 v[32:47], v[196:199], v[212:215], v[32:47]
	ds_read_b128 v[212:215], v173 offset:57344
	v_exp_f32_e32 v86, v86
	v_exp_f32_e32 v87, v87
	s_waitcnt lgkmcnt(10)
	v_mfma_f32_32x32x16_bf16 v[16:31], v[184:187], v[230:233], v[16:31]
	ds_read_b128 v[230:233], v174 offset:49152
	v_exp_f32_e32 v88, v88
	v_exp_f32_e32 v89, v89
	s_waitcnt lgkmcnt(9)
	v_mfma_f32_32x32x16_bf16 v[16:31], v[188:191], v[234:237], v[16:31]
	ds_read_b128 v[234:237], v174 offset:57344
	v_exp_f32_e32 v90, v90
	v_exp_f32_e32 v91, v91
	s_waitcnt lgkmcnt(7)
	v_mfma_f32_32x32x16_bf16 v[16:31], v[192:195], v[238:241], v[16:31]
	ds_read_b128 v[238:241], v175 offset:49152
	v_exp_f32_e32 v92, v92
	v_exp_f32_e32 v93, v93
	s_waitcnt lgkmcnt(5)
	v_mfma_f32_32x32x16_bf16 v[16:31], v[196:199], v[242:245], v[16:31]
	ds_read_b128 v[242:245], v175 offset:57344
	v_exp_f32_e32 v94, v94
	v_exp_f32_e32 v95, v95
	s_barrier
; #define SBAR() __builtin_amdgcn_sched_barrier(0)
;     ...
;   { SBAR(); qkt(pB0, pB1, KSUB(1, 1), qr, r32, hi);
;     finishSM(pA0, pA1, alA, l_reg, pa0, pa1, pa2, pa3); SBAR();
;     pv_d0(o, VSUB(1, 0), pa0, pa1, pa2, pa3); partialSM(pB0, pB1, m_reg, mnB, alB);
	v_mfma_f32_32x32x16_bf16 v[128:143], v[200:203], v[124:127], 0
	ds_read_b128 v[200:203], v176 offset:49152
	v_cvt_pk_bf16_f32 v184, v64, v65
	v_add_f32_e32 v169, v169, v64
	v_add_f32_e32 v219, v219, v65
	v_mfma_f32_32x32x16_bf16 v[144:159], v[204:207], v[124:127], 0
	ds_read_b128 v[204:207], v176 offset:57344
	v_cvt_pk_bf16_f32 v185, v66, v67
	v_add_f32_e32 v222, v222, v66
	v_add_f32_e32 v254, v254, v67
	s_waitcnt lgkmcnt(7)
	v_mfma_f32_32x32x16_bf16 v[128:143], v[208:211], v[120:123], v[128:143]
	ds_read_b128 v[208:211], v177 offset:49152
	v_cvt_pk_bf16_f32 v186, v68, v69
	v_add_f32_e32 v169, v169, v68
	v_add_f32_e32 v219, v219, v69
	s_waitcnt lgkmcnt(7)
	v_mfma_f32_32x32x16_bf16 v[144:159], v[212:215], v[120:123], v[144:159]
	ds_read_b128 v[212:215], v177 offset:57344
	v_cvt_pk_bf16_f32 v187, v70, v71
	v_add_f32_e32 v222, v222, v70
	v_add_f32_e32 v254, v254, v71
	s_waitcnt lgkmcnt(7)
	v_mfma_f32_32x32x16_bf16 v[128:143], v[230:233], v[116:119], v[128:143]
	ds_read_b128 v[230:233], v178 offset:49152
	v_cvt_pk_bf16_f32 v188, v72, v73
	v_add_f32_e32 v169, v169, v72
	v_add_f32_e32 v219, v219, v73
	v_permlane32_swap_b32_e32 v184, v186
	s_waitcnt lgkmcnt(7)
	v_mfma_f32_32x32x16_bf16 v[144:159], v[234:237], v[116:119], v[144:159]
	ds_read_b128 v[234:237], v178 offset:57344
	v_cvt_pk_bf16_f32 v189, v74, v75
	v_add_f32_e32 v222, v222, v74
	v_add_f32_e32 v254, v254, v75
	v_permlane32_swap_b32_e32 v185, v187
	s_waitcnt lgkmcnt(7)
	v_mfma_f32_32x32x16_bf16 v[128:143], v[238:241], v[112:115], v[128:143]
	ds_read_b128 v[238:241], v179 offset:49152
	v_cvt_pk_bf16_f32 v190, v76, v77
	v_add_f32_e32 v169, v169, v76
	v_add_f32_e32 v219, v219, v77
	s_waitcnt lgkmcnt(7)
	v_mfma_f32_32x32x16_bf16 v[144:159], v[242:245], v[112:115], v[144:159]
	ds_read_b128 v[242:245], v179 offset:57344
	v_cvt_pk_bf16_f32 v191, v78, v79
	v_add_f32_e32 v222, v222, v78
	v_add_f32_e32 v254, v254, v79
	s_waitcnt lgkmcnt(7)
	v_mfma_f32_32x32x16_bf16 v[128:143], v[200:203], v[108:111], v[128:143]
	v_cvt_pk_bf16_f32 v192, v80, v81
	v_add_f32_e32 v169, v169, v80
	v_add_f32_e32 v219, v219, v81
	v_permlane32_swap_b32_e32 v188, v190
	s_waitcnt lgkmcnt(6)
	v_mfma_f32_32x32x16_bf16 v[144:159], v[204:207], v[108:111], v[144:159]
	v_cvt_pk_bf16_f32 v193, v82, v83
	v_add_f32_e32 v222, v222, v82
	v_add_f32_e32 v254, v254, v83
	v_permlane32_swap_b32_e32 v189, v191
	s_waitcnt lgkmcnt(5)
	v_mfma_f32_32x32x16_bf16 v[128:143], v[208:211], v[104:107], v[128:143]
	v_cvt_pk_bf16_f32 v194, v84, v85
	v_add_f32_e32 v169, v169, v84
	v_add_f32_e32 v219, v219, v85
	s_waitcnt lgkmcnt(4)
	v_mfma_f32_32x32x16_bf16 v[144:159], v[212:215], v[104:107], v[144:159]
	ds_read_b64_tr_b16 v[200:201], v182 offset:32768
	ds_read_b64_tr_b16 v[202:203], v182 offset:34816
	v_cvt_pk_bf16_f32 v195, v86, v87
	v_add_f32_e32 v222, v222, v86
	v_add_f32_e32 v254, v254, v87
	s_waitcnt lgkmcnt(5)
	v_mfma_f32_32x32x16_bf16 v[128:143], v[230:233], v[100:103], v[128:143]
	ds_read_b64_tr_b16 v[204:205], v182 offset:36864
	ds_read_b64_tr_b16 v[206:207], v182 offset:38912
	v_cvt_pk_bf16_f32 v196, v88, v89
	v_add_f32_e32 v169, v169, v88
	v_add_f32_e32 v219, v219, v89
	v_permlane32_swap_b32_e32 v192, v194
	s_waitcnt lgkmcnt(6)
	v_mfma_f32_32x32x16_bf16 v[144:159], v[234:237], v[100:103], v[144:159]
	ds_read_b64_tr_b16 v[208:209], v182 offset:40960
	ds_read_b64_tr_b16 v[210:211], v182 offset:43008
	v_cvt_pk_bf16_f32 v197, v90, v91
	v_add_f32_e32 v222, v222, v90
	v_add_f32_e32 v254, v254, v91
	v_permlane32_swap_b32_e32 v193, v195
	s_waitcnt lgkmcnt(7)
	v_mfma_f32_32x32x16_bf16 v[128:143], v[238:241], v[96:99], v[128:143]
	ds_read_b64_tr_b16 v[212:213], v182 offset:45056
	ds_read_b64_tr_b16 v[214:215], v182 offset:47104
	v_cvt_pk_bf16_f32 v198, v92, v93
	v_add_f32_e32 v169, v169, v92
	v_add_f32_e32 v219, v219, v93
	s_waitcnt lgkmcnt(8)
	v_mfma_f32_32x32x16_bf16 v[144:159], v[242:245], v[96:99], v[144:159]
	ds_read_b64_tr_b16 v[230:231], v182 offset:33280
	ds_read_b64_tr_b16 v[232:233], v182 offset:35328
	v_cvt_pk_bf16_f32 v199, v94, v95
	v_add_f32_e32 v222, v222, v94
	v_add_f32_e32 v254, v254, v95
	v_permlane32_swap_b32_e32 v196, v198
	v_permlane32_swap_b32_e32 v197, v199
	s_waitcnt lgkmcnt(8)
	v_mfma_f32_32x32x16_bf16 v[0:15], v[184:187], v[200:203], v[0:15]
	ds_read_b64_tr_b16 v[234:235], v182 offset:37376
	ds_read_b64_tr_b16 v[236:237], v182 offset:39424
	v_exp_f32_e32 v128, v128
	v_exp_f32_e32 v129, v129
	s_waitcnt lgkmcnt(8)
	v_mfma_f32_32x32x16_bf16 v[0:15], v[188:191], v[204:207], v[0:15]
	ds_read_b64_tr_b16 v[238:239], v182 offset:41472
	ds_read_b64_tr_b16 v[240:241], v182 offset:43520
	v_exp_f32_e32 v130, v130
	v_exp_f32_e32 v131, v131
	s_waitcnt lgkmcnt(8)
	v_mfma_f32_32x32x16_bf16 v[0:15], v[192:195], v[208:211], v[0:15]
	ds_read_b64_tr_b16 v[242:243], v182 offset:45568
	ds_read_b64_tr_b16 v[244:245], v182 offset:47616
	v_exp_f32_e32 v132, v132
	v_exp_f32_e32 v133, v133
	s_waitcnt lgkmcnt(8)
	v_mfma_f32_32x32x16_bf16 v[0:15], v[196:199], v[212:215], v[0:15]
	ds_read_b64_tr_b16 v[200:201], v182 offset:33792
	ds_read_b64_tr_b16 v[202:203], v182 offset:35840
	v_exp_f32_e32 v134, v134
	v_exp_f32_e32 v135, v135
	s_waitcnt lgkmcnt(8)
	v_mfma_f32_32x32x16_bf16 v[48:63], v[184:187], v[230:233], v[48:63]
	ds_read_b64_tr_b16 v[204:205], v182 offset:37888
	ds_read_b64_tr_b16 v[206:207], v182 offset:39936
	v_exp_f32_e32 v136, v136
	v_exp_f32_e32 v137, v137
	s_waitcnt lgkmcnt(8)
	v_mfma_f32_32x32x16_bf16 v[48:63], v[188:191], v[234:237], v[48:63]
	ds_read_b64_tr_b16 v[208:209], v182 offset:41984
	ds_read_b64_tr_b16 v[210:211], v182 offset:44032
	v_exp_f32_e32 v138, v138
	v_exp_f32_e32 v139, v139
	s_waitcnt lgkmcnt(8)
;     ...
;     pv_d0(o, VSUB(1, 0), pa0, pa1, pa2, pa3); partialSM(pB0, pB1, m_reg, mnB, alB);
	v_mfma_f32_32x32x16_bf16 v[48:63], v[192:195], v[238:241], v[48:63]
	ds_read_b64_tr_b16 v[212:213], v182 offset:46080
	ds_read_b64_tr_b16 v[214:215], v182 offset:48128
	v_exp_f32_e32 v140, v140
	v_exp_f32_e32 v141, v141
	s_waitcnt lgkmcnt(8)
	v_mfma_f32_32x32x16_bf16 v[48:63], v[196:199], v[242:245], v[48:63]
	ds_read_b64_tr_b16 v[230:231], v182 offset:34304
	ds_read_b64_tr_b16 v[232:233], v182 offset:36352
	v_exp_f32_e32 v142, v142
	v_exp_f32_e32 v143, v143
	s_waitcnt lgkmcnt(8)
	v_mfma_f32_32x32x16_bf16 v[32:47], v[184:187], v[200:203], v[32:47]
	ds_read_b64_tr_b16 v[234:235], v182 offset:38400
	ds_read_b64_tr_b16 v[236:237], v182 offset:40448
	v_exp_f32_e32 v144, v144
	v_exp_f32_e32 v145, v145
	s_waitcnt lgkmcnt(8)
	v_mfma_f32_32x32x16_bf16 v[32:47], v[188:191], v[204:207], v[32:47]
	ds_read_b64_tr_b16 v[238:239], v182 offset:42496
	ds_read_b64_tr_b16 v[240:241], v182 offset:44544
	v_exp_f32_e32 v146, v146
	v_exp_f32_e32 v147, v147
	s_waitcnt lgkmcnt(8)
	v_mfma_f32_32x32x16_bf16 v[32:47], v[192:195], v[208:211], v[32:47]
	ds_read_b64_tr_b16 v[242:243], v182 offset:46592
	ds_read_b64_tr_b16 v[244:245], v182 offset:48640
	v_exp_f32_e32 v148, v148
	v_exp_f32_e32 v149, v149
	s_waitcnt lgkmcnt(8)
	v_mfma_f32_32x32x16_bf16 v[32:47], v[196:199], v[212:215], v[32:47]
	v_exp_f32_e32 v150, v150
	v_exp_f32_e32 v151, v151
	s_waitcnt lgkmcnt(6)
	v_mfma_f32_32x32x16_bf16 v[16:31], v[184:187], v[230:233], v[16:31]
	v_exp_f32_e32 v152, v152
	v_exp_f32_e32 v153, v153
	s_waitcnt lgkmcnt(4)
	v_mfma_f32_32x32x16_bf16 v[16:31], v[188:191], v[234:237], v[16:31]
	v_exp_f32_e32 v154, v154
	v_exp_f32_e32 v155, v155
	s_waitcnt lgkmcnt(2)
	v_mfma_f32_32x32x16_bf16 v[16:31], v[192:195], v[238:241], v[16:31]
	v_exp_f32_e32 v156, v156
	v_exp_f32_e32 v157, v157
	s_waitcnt lgkmcnt(0)
	v_mfma_f32_32x32x16_bf16 v[16:31], v[196:199], v[242:245], v[16:31]
	v_exp_f32_e32 v158, v158
	v_exp_f32_e32 v159, v159
	s_waitcnt lgkmcnt(0)
	s_barrier
; #define SBAR() __builtin_amdgcn_sched_barrier(0)
; __device__ __forceinline__ void finishSM(f32x16& p0, f32x16& p1, float alpha, float& l_reg, bf16x8& pa0, bf16x8& pa1, bf16x8& pa2, bf16x8& pa3) {
;     ...
;   { auto rr = __builtin_amdgcn_permlane32_swap(__float_as_uint(ps), __float_as_uint(ps), false, false);
;     ps = __uint_as_float(rr[0]) + __uint_as_float(rr[1]); }
;   l_reg = l_reg * alpha + ps;
;     ...
;     finishSM(pB0, pB1, alB, l_reg, pa0, pa1, pa2, pa3); SBAR();
;     pv_d0(o, VSUB(1, 1), pa0, pa1, pa2, pa3); }
;     ...
;   if (hi == 0) li_l[r32] = l_reg; asm volatile("s_waitcnt lgkmcnt(0)" ::: "memory");
	v_cvt_pk_bf16_f32 v184, v128, v129
	v_add_f32_e32 v169, v169, v128
	v_add_f32_e32 v219, v219, v129
	v_cvt_pk_bf16_f32 v185, v130, v131
	v_add_f32_e32 v222, v222, v130
	v_add_f32_e32 v254, v254, v131
	v_cvt_pk_bf16_f32 v186, v132, v133
	v_add_f32_e32 v169, v169, v132
	v_add_f32_e32 v219, v219, v133
	v_cvt_pk_bf16_f32 v187, v134, v135
	v_add_f32_e32 v222, v222, v134
	v_add_f32_e32 v254, v254, v135
	v_cvt_pk_bf16_f32 v188, v136, v137
	v_add_f32_e32 v169, v169, v136
	v_add_f32_e32 v219, v219, v137
	v_permlane32_swap_b32_e32 v184, v186
	v_cvt_pk_bf16_f32 v189, v138, v139
	v_add_f32_e32 v222, v222, v138
	v_add_f32_e32 v254, v254, v139
	v_permlane32_swap_b32_e32 v185, v187
	v_cvt_pk_bf16_f32 v190, v140, v141
	v_add_f32_e32 v169, v169, v140
	v_add_f32_e32 v219, v219, v141
	v_cvt_pk_bf16_f32 v191, v142, v143
	v_add_f32_e32 v222, v222, v142
	v_add_f32_e32 v254, v254, v143
	v_cvt_pk_bf16_f32 v192, v144, v145
	v_add_f32_e32 v169, v169, v144
	v_add_f32_e32 v219, v219, v145
	v_permlane32_swap_b32_e32 v188, v190
	v_cvt_pk_bf16_f32 v193, v146, v147
	v_add_f32_e32 v222, v222, v146
	v_add_f32_e32 v254, v254, v147
	v_permlane32_swap_b32_e32 v189, v191
	v_cvt_pk_bf16_f32 v194, v148, v149
	v_add_f32_e32 v169, v169, v148
	v_add_f32_e32 v219, v219, v149
	ds_read_b64_tr_b16 v[200:201], v182 offset:49152
	ds_read_b64_tr_b16 v[202:203], v182 offset:51200
	v_cvt_pk_bf16_f32 v195, v150, v151
	v_add_f32_e32 v222, v222, v150
	v_add_f32_e32 v254, v254, v151
	ds_read_b64_tr_b16 v[204:205], v182 offset:53248
	ds_read_b64_tr_b16 v[206:207], v182 offset:55296
	v_cvt_pk_bf16_f32 v196, v152, v153
	v_add_f32_e32 v169, v169, v152
	v_add_f32_e32 v219, v219, v153
	v_permlane32_swap_b32_e32 v192, v194
	ds_read_b64_tr_b16 v[208:209], v182 offset:57344
	ds_read_b64_tr_b16 v[210:211], v182 offset:59392
	v_cvt_pk_bf16_f32 v197, v154, v155
	v_add_f32_e32 v222, v222, v154
	v_add_f32_e32 v254, v254, v155
	v_permlane32_swap_b32_e32 v193, v195
	ds_read_b64_tr_b16 v[212:213], v182 offset:61440
	ds_read_b64_tr_b16 v[214:215], v182 offset:63488
	v_cvt_pk_bf16_f32 v198, v156, v157
	v_add_f32_e32 v169, v169, v156
	v_add_f32_e32 v219, v219, v157
	ds_read_b64_tr_b16 v[230:231], v182 offset:49664
	ds_read_b64_tr_b16 v[232:233], v182 offset:51712
	v_cvt_pk_bf16_f32 v199, v158, v159
	v_add_f32_e32 v222, v222, v158
	v_add_f32_e32 v254, v254, v159
	v_permlane32_swap_b32_e32 v196, v198
	v_permlane32_swap_b32_e32 v197, v199
	s_waitcnt lgkmcnt(8)
	v_mfma_f32_32x32x16_bf16 v[0:15], v[184:187], v[200:203], v[0:15]
	ds_read_b64_tr_b16 v[234:235], v182 offset:53760
	ds_read_b64_tr_b16 v[236:237], v182 offset:55808
	s_waitcnt lgkmcnt(8)
	v_mfma_f32_32x32x16_bf16 v[0:15], v[188:191], v[204:207], v[0:15]
	ds_read_b64_tr_b16 v[238:239], v182 offset:57856
	ds_read_b64_tr_b16 v[240:241], v182 offset:59904
	s_waitcnt lgkmcnt(8)
	v_mfma_f32_32x32x16_bf16 v[0:15], v[192:195], v[208:211], v[0:15]
	ds_read_b64_tr_b16 v[242:243], v182 offset:61952
	ds_read_b64_tr_b16 v[244:245], v182 offset:64000
	s_waitcnt lgkmcnt(8)
	v_mfma_f32_32x32x16_bf16 v[0:15], v[196:199], v[212:215], v[0:15]
	ds_read_b64_tr_b16 v[200:201], v182 offset:50176
	ds_read_b64_tr_b16 v[202:203], v182 offset:52224
	s_waitcnt lgkmcnt(8)
	v_mfma_f32_32x32x16_bf16 v[48:63], v[184:187], v[230:233], v[48:63]
	ds_read_b64_tr_b16 v[204:205], v182 offset:54272
	ds_read_b64_tr_b16 v[206:207], v182 offset:56320
	s_waitcnt lgkmcnt(8)
	v_mfma_f32_32x32x16_bf16 v[48:63], v[188:191], v[234:237], v[48:63]
	ds_read_b64_tr_b16 v[208:209], v182 offset:58368
	ds_read_b64_tr_b16 v[210:211], v182 offset:60416
	s_waitcnt lgkmcnt(8)
	v_mfma_f32_32x32x16_bf16 v[48:63], v[192:195], v[238:241], v[48:63]
	ds_read_b64_tr_b16 v[212:213], v182 offset:62464
	ds_read_b64_tr_b16 v[214:215], v182 offset:64512
	s_waitcnt lgkmcnt(8)
	v_mfma_f32_32x32x16_bf16 v[48:63], v[196:199], v[242:245], v[48:63]
	ds_read_b64_tr_b16 v[230:231], v182 offset:50688
	ds_read_b64_tr_b16 v[232:233], v182 offset:52736
	s_waitcnt lgkmcnt(8)
	v_mfma_f32_32x32x16_bf16 v[32:47], v[184:187], v[200:203], v[32:47]
	ds_read_b64_tr_b16 v[234:235], v182 offset:54784
	ds_read_b64_tr_b16 v[236:237], v182 offset:56832
	s_waitcnt lgkmcnt(8)
	v_mfma_f32_32x32x16_bf16 v[32:47], v[188:191], v[204:207], v[32:47]
	ds_read_b64_tr_b16 v[238:239], v182 offset:58880
	ds_read_b64_tr_b16 v[240:241], v182 offset:60928
	s_waitcnt lgkmcnt(8)
	v_mfma_f32_32x32x16_bf16 v[32:47], v[192:195], v[208:211], v[32:47]
	ds_read_b64_tr_b16 v[242:243], v182 offset:62976
	ds_read_b64_tr_b16 v[244:245], v182 offset:65024
	s_waitcnt lgkmcnt(8)
	v_mfma_f32_32x32x16_bf16 v[32:47], v[196:199], v[212:215], v[32:47]
	s_waitcnt lgkmcnt(6)
	v_mfma_f32_32x32x16_bf16 v[16:31], v[184:187], v[230:233], v[16:31]
	s_waitcnt lgkmcnt(4)
	v_mfma_f32_32x32x16_bf16 v[16:31], v[188:191], v[234:237], v[16:31]
	s_waitcnt lgkmcnt(2)
	v_mfma_f32_32x32x16_bf16 v[16:31], v[192:195], v[238:241], v[16:31]
	s_waitcnt lgkmcnt(0)
	v_mfma_f32_32x32x16_bf16 v[16:31], v[196:199], v[242:245], v[16:31]
	s_waitcnt lgkmcnt(0)
	s_barrier
	s_setprio 0
	v_add_f32_e32 v169, v169, v219
	v_add_f32_e32 v222, v222, v254
	v_add_f32_e32 v169, v169, v222
	v_mov_b32_e32 v219, v169
	s_nop 1
	v_permlane32_swap_b32_e32 v169, v219
	v_add_f32_e32 v64, v169, v219
	v_lshlrev_b32_e32 v164, 4, v229
	v_mov_b32_e32 v165, 0
	s_and_saveexec_b64 s[0:1], s[2:3]
	ds_write_b32 v168, v64
	s_branch .LBB0_477
